# gates epilogue: first UC row-group loads hoisted above the wait on gate constants (on top of v29 ring2r)
# speedup vs baseline: 1.0075x; 1.0035x over previous
; #define PG8_STAGE(bufoff, gbase, voff) do { _Pragma("unroll") for (int _i = 0; _i < 2; ++_i) \
;         __builtin_amdgcn_global_load_lds((const unsigned*)((const char*)(gbase) + (voff)[_i]), (LAS unsigned*)(lds + (bufoff) + ldsw + _i * 8192), 16, 0, 0); } while (0)
; #define PG8_LDA(dst, b, h) do { _Pragma("unroll") for (int m = 0; m < 4; ++m) _Pragma("unroll") for (int k = 0; k < 2; ++k) dst[m][k] = *(const LAS bf16x8*)(lds + PG8_SA(b, h) + aoff + m * 2048 + k * 1024); } while (0)
; #define PG8_LDB(dst, b, h) do { _Pragma("unroll") for (int n = 0; n < 2; ++n) _Pragma("unroll") for (int k = 0; k < 2; ++k) dst[n][k] = *(const LAS bf16x8*)(lds + PG8_SB(b, h) + boff + n * 2048 + k * 1024); } while (0)
; #define PG8_WAIT_V(n) asm volatile("s_waitcnt vmcnt(" #n ")" ::: "memory")
; #define PG8_WAIT_L(n) asm volatile("s_waitcnt lgkmcnt(" #n ")" ::: "memory")
;     ...
;         const char* nA = has_next ? PG8_APTR(nxt) : cA; const char* nB = has_next ? PG8_BPTR(nxt) : cB;
;         for (int t = 0; t < nt; t += 2) {
;             const bool last = (t == nt - 2);
;             const char* a1 = cA + (size_t)(t + 1) * kstep;
;             const char* a2 = last ? nA : cA + (size_t)(t + 2) * kstep; const char* b2 = last ? nB : cB + (size_t)(t + 2) * kstep;
;             const char* a3 = a2 + kstep; const char* b3 = b2 + kstep;
;             if constexpr (SP2) {
;             PG8_LDB(B0, 0, 0); PG8_LDB(B1, 0, 1); PG8_SCHED; PG8_LDA(At, 0, 0); PG8_STAGE(PG8_SA(1, 1), a1 + hstepA, voffA);
;             PG8_WAIT_V(8); PG8_WAIT_L(0); PG8_BAR; PG8_MMA(0, 0, At, B0); PG8_MMA(0, 1, At, B1); PG8_BAR; PG8_SCHED;
;             PG8_LDA(At, 0, 1); PG8_STAGE(PG8_SB(0, 0), b2, voffB); PG8_STAGE(PG8_SB(0, 1), b2 + hstepB, voffB); PG8_STAGE(PG8_SA(0, 0), a2, voffA);
;             PG8_WAIT_V(8); PG8_WAIT_L(0); PG8_BAR; PG8_MMA(1, 0, At, B0); PG8_MMA(1, 1, At, B1); PG8_BAR; PG8_SCHED;
;             PG8_LDB(B0, 1, 0); PG8_LDB(B1, 1, 1); PG8_SCHED; PG8_LDA(At, 1, 0); PG8_STAGE(PG8_SA(0, 1), a2 + hstepA, voffA);
;             PG8_WAIT_V(8); PG8_WAIT_L(0); PG8_BAR; PG8_MMA(0, 0, At, B0); PG8_MMA(0, 1, At, B1); PG8_BAR; PG8_SCHED;
;             PG8_LDA(At, 1, 1); PG8_STAGE(PG8_SB(1, 0), b3, voffB); PG8_STAGE(PG8_SB(1, 1), b3 + hstepB, voffB); PG8_STAGE(PG8_SA(1, 0), a3, voffA);
;             PG8_WAIT_V(8); PG8_WAIT_L(0); PG8_BAR; PG8_MMA(1, 0, At, B0); PG8_MMA(1, 1, At, B1); PG8_BAR; PG8_SCHED;
.LBB9_867:
	s_ashr_i32 s19, s18, 31
	s_lshl_b64 s[22:23], s[18:19], 17
	s_add_u32 s22, s30, s22
	s_addc_u32 s23, s31, s23
	s_and_b64 s[0:1], s[0:1], exec
	s_cselect_b32 s1, s23, s27
	s_cselect_b32 s0, s22, s26
	s_add_i32 s57, 0, 0x10000
	s_add_i32 s65, 0, 0x14000
	v_add_u32_e32 v188, s57, v156
	v_add_u32_e32 v189, s65, v156
	ds_read_b128 v[2:5], v188
	ds_read_b128 v[6:9], v188 offset:1024
	ds_read_b128 v[10:13], v188 offset:2048
	ds_read_b128 v[14:17], v188 offset:3072
	ds_read_b128 v[18:21], v189
	ds_read_b128 v[22:25], v189 offset:1024
	ds_read_b128 v[26:29], v189 offset:2048
	ds_read_b128 v[30:33], v189 offset:3072
	s_add_u32 s54, s24, 0xb0080
	s_addc_u32 s55, s25, 0
	s_add_i32 s66, s34, 0xc000
	v_lshl_add_u64 v[66:67], s[54:55], 0, v[150:151]
	s_mov_b32 m0, s66
	s_add_i32 s19, s34, 0xe000
	ds_read_b128 v[34:37], v157
	ds_read_b128 v[38:41], v157 offset:1024
	ds_read_b128 v[42:45], v157 offset:2048
	ds_read_b128 v[46:49], v157 offset:3072
	ds_read_b128 v[50:53], v157 offset:4096
	ds_read_b128 v[54:57], v157 offset:5120
	ds_read_b128 v[58:61], v157 offset:6144
	ds_read_b128 v[62:65], v157 offset:7168
	global_load_lds_dwordx4 v[66:67], off
	v_lshl_add_u64 v[66:67], s[54:55], 0, v[148:149]
	s_mov_b32 m0, s19
	s_nop 0
	global_load_lds_dwordx4 v[66:67], off
	s_waitcnt vmcnt(8)
	s_waitcnt lgkmcnt(0)
	s_barrier
	s_setprio 1
	s_waitcnt lgkmcnt(0)
	v_mfma_f32_16x16x32_bf16 v[66:69], v[2:5], v[34:37], 0
	v_mfma_f32_16x16x32_bf16 v[70:73], v[10:13], v[34:37], 0
	v_mfma_f32_16x16x32_bf16 v[74:77], v[2:5], v[42:45], 0
	v_mfma_f32_16x16x32_bf16 v[78:81], v[10:13], v[42:45], 0
	v_mfma_f32_16x16x32_bf16 v[82:85], v[2:5], v[50:53], 0
	v_mfma_f32_16x16x32_bf16 v[86:89], v[10:13], v[50:53], 0
	v_mfma_f32_16x16x32_bf16 v[90:93], v[2:5], v[58:61], 0
	v_mfma_f32_16x16x32_bf16 v[94:97], v[10:13], v[58:61], 0
	v_mfma_f32_16x16x32_bf16 v[66:69], v[6:9], v[38:41], v[66:69]
	v_mfma_f32_16x16x32_bf16 v[70:73], v[14:17], v[38:41], v[70:73]
	v_mfma_f32_16x16x32_bf16 v[74:77], v[6:9], v[46:49], v[74:77]
	v_mfma_f32_16x16x32_bf16 v[78:81], v[14:17], v[46:49], v[78:81]
	v_mfma_f32_16x16x32_bf16 v[82:85], v[6:9], v[54:57], v[82:85]
	v_mfma_f32_16x16x32_bf16 v[86:89], v[14:17], v[54:57], v[86:89]
	v_mfma_f32_16x16x32_bf16 v[90:93], v[6:9], v[62:65], v[90:93]
	v_mfma_f32_16x16x32_bf16 v[94:97], v[14:17], v[62:65], v[94:97]
	s_setprio 0
	s_setprio 1
	v_mfma_f32_16x16x32_bf16 v[98:101], v[18:21], v[34:37], 0
	v_mfma_f32_16x16x32_bf16 v[34:37], v[26:29], v[34:37], 0
	v_mfma_f32_16x16x32_bf16 v[98:101], v[22:25], v[38:41], v[98:101]
	v_mfma_f32_16x16x32_bf16 v[34:37], v[30:33], v[38:41], v[34:37]
	v_mfma_f32_16x16x32_bf16 v[38:41], v[18:21], v[42:45], 0
	v_mfma_f32_16x16x32_bf16 v[42:45], v[26:29], v[42:45], 0
	v_mfma_f32_16x16x32_bf16 v[38:41], v[22:25], v[46:49], v[38:41]
	v_mfma_f32_16x16x32_bf16 v[42:45], v[30:33], v[46:49], v[42:45]
	v_mfma_f32_16x16x32_bf16 v[46:49], v[18:21], v[50:53], 0
	v_mfma_f32_16x16x32_bf16 v[50:53], v[26:29], v[50:53], 0
	v_mfma_f32_16x16x32_bf16 v[46:49], v[22:25], v[54:57], v[46:49]
	v_mfma_f32_16x16x32_bf16 v[50:53], v[30:33], v[54:57], v[50:53]
	v_mfma_f32_16x16x32_bf16 v[54:57], v[18:21], v[58:61], 0
	v_mfma_f32_16x16x32_bf16 v[58:61], v[26:29], v[58:61], 0
	v_mfma_f32_16x16x32_bf16 v[54:57], v[22:25], v[62:65], v[54:57]
	v_mfma_f32_16x16x32_bf16 v[58:61], v[30:33], v[62:65], v[58:61]
	s_setprio 0
	s_barrier
	s_add_i32 s57, s57, s33
	v_lshl_add_u64 v[206:207], s[26:27], 0, v[186:187]
	s_add_i32 s53, s57, 0x2000
	v_lshl_add_u64 v[130:131], v[206:207], 0, s[88:89]
	s_mov_b32 m0, s57
	v_lshl_add_u64 v[208:209], s[26:27], 0, v[146:147]
	s_add_u32 s68, s26, 0x10100
	ds_read_b128 v[62:65], v157 offset:16384
	ds_read_b128 v[102:105], v157 offset:17408
	ds_read_b128 v[106:109], v157 offset:18432
	ds_read_b128 v[110:113], v157 offset:19456
	ds_read_b128 v[114:117], v157 offset:20480
	ds_read_b128 v[118:121], v157 offset:21504
	ds_read_b128 v[122:125], v157 offset:22528
	ds_read_b128 v[126:129], v157 offset:23552
	global_load_lds_dwordx4 v[130:131], off
	v_lshl_add_u64 v[130:131], v[208:209], 0, s[88:89]
	s_mov_b32 m0, s53
	s_addc_u32 s69, s27, 0
	s_add_i32 s54, s65, s33
	global_load_lds_dwordx4 v[130:131], off
	v_lshl_add_u64 v[130:131], s[68:69], 0, v[186:187]
	s_mov_b32 m0, s54
	s_add_i32 s55, s54, 0x2000
	global_load_lds_dwordx4 v[130:131], off
	v_lshl_add_u64 v[130:131], s[68:69], 0, v[146:147]
	s_mov_b32 m0, s55
	v_lshl_add_u64 v[210:211], s[24:25], 0, v[150:151]
	global_load_lds_dwordx4 v[130:131], off
	v_lshl_add_u64 v[130:131], v[210:211], 0, s[88:89]
	s_mov_b32 m0, s34
	v_lshl_add_u64 v[212:213], s[24:25], 0, v[148:149]
	global_load_lds_dwordx4 v[130:131], off
	v_lshl_add_u64 v[130:131], v[212:213], 0, s[88:89]
	s_mov_b32 m0, s35
	s_nop 0
	global_load_lds_dwordx4 v[130:131], off
	s_waitcnt vmcnt(8)
	s_waitcnt lgkmcnt(0)
	s_barrier
; #define PG8_STAGE(bufoff, gbase, voff) do { _Pragma("unroll") for (int _i = 0; _i < 2; ++_i) \
;         __builtin_amdgcn_global_load_lds((const unsigned*)((const char*)(gbase) + (voff)[_i]), (LAS unsigned*)(lds + (bufoff) + ldsw + _i * 8192), 16, 0, 0); } while (0)
; #define PG8_LDA(dst, b, h) do { _Pragma("unroll") for (int m = 0; m < 4; ++m) _Pragma("unroll") for (int k = 0; k < 2; ++k) dst[m][k] = *(const LAS bf16x8*)(lds + PG8_SA(b, h) + aoff + m * 2048 + k * 1024); } while (0)
; #define PG8_LDB(dst, b, h) do { _Pragma("unroll") for (int n = 0; n < 2; ++n) _Pragma("unroll") for (int k = 0; k < 2; ++k) dst[n][k] = *(const LAS bf16x8*)(lds + PG8_SB(b, h) + boff + n * 2048 + k * 1024); } while (0)
; #define PG8_MMA(ai, bj, At, Bt) do { __builtin_amdgcn_s_setprio(1); _Pragma("unroll") for (int m = 0; m < 4; ++m) _Pragma("unroll") for (int n = 0; n < 2; ++n) _Pragma("unroll") for (int k = 0; k < 2; ++k) \
;         acc[ai][bj][m][n] = __builtin_amdgcn_mfma_f32_16x16x32_bf16(Bt[n][k], At[m][k], acc[ai][bj][m][n], 0, 0, 0); __builtin_amdgcn_s_setprio(0); } while (0)
; #define PG8_WAIT_V(n) asm volatile("s_waitcnt vmcnt(" #n ")" ::: "memory")
; #define PG8_WAIT_L(n) asm volatile("s_waitcnt lgkmcnt(" #n ")" ::: "memory")
; #define PG8_BAR __builtin_amdgcn_s_barrier()
;     ...
;             if constexpr (SP2) {
;             PG8_LDB(B0, 0, 0); PG8_LDB(B1, 0, 1); PG8_SCHED; PG8_LDA(At, 0, 0); PG8_STAGE(PG8_SA(1, 1), a1 + hstepA, voffA);
;             PG8_WAIT_V(8); PG8_WAIT_L(0); PG8_BAR; PG8_MMA(0, 0, At, B0); PG8_MMA(0, 1, At, B1); PG8_BAR; PG8_SCHED;
;             PG8_LDA(At, 0, 1); PG8_STAGE(PG8_SB(0, 0), b2, voffB); PG8_STAGE(PG8_SB(0, 1), b2 + hstepB, voffB); PG8_STAGE(PG8_SA(0, 0), a2, voffA);
;             PG8_WAIT_V(8); PG8_WAIT_L(0); PG8_BAR; PG8_MMA(1, 0, At, B0); PG8_MMA(1, 1, At, B1); PG8_BAR; PG8_SCHED;
;             PG8_LDB(B0, 1, 0); PG8_LDB(B1, 1, 1); PG8_SCHED; PG8_LDA(At, 1, 0); PG8_STAGE(PG8_SA(0, 1), a2 + hstepA, voffA);
;             PG8_WAIT_V(8); PG8_WAIT_L(0); PG8_BAR; PG8_MMA(0, 0, At, B0); PG8_MMA(0, 1, At, B1); PG8_BAR; PG8_SCHED;
;             PG8_LDA(At, 1, 1); PG8_STAGE(PG8_SB(1, 0), b3, voffB); PG8_STAGE(PG8_SB(1, 1), b3 + hstepB, voffB); PG8_STAGE(PG8_SA(1, 0), a3, voffA);
;             PG8_WAIT_V(8); PG8_WAIT_L(0); PG8_BAR; PG8_MMA(1, 0, At, B0); PG8_MMA(1, 1, At, B1); PG8_BAR; PG8_SCHED;
	s_setprio 1
	s_waitcnt lgkmcnt(0)
	v_mfma_f32_16x16x32_bf16 v[130:133], v[2:5], v[62:65], 0
	v_mfma_f32_16x16x32_bf16 v[138:141], v[2:5], v[106:109], 0
	v_mfma_f32_16x16x32_bf16 v[152:155], v[2:5], v[114:117], 0
	v_mfma_f32_16x16x32_bf16 v[2:5], v[2:5], v[122:125], 0
	v_mfma_f32_16x16x32_bf16 v[130:133], v[6:9], v[102:105], v[130:133]
	v_mfma_f32_16x16x32_bf16 v[134:137], v[10:13], v[62:65], 0
	v_mfma_f32_16x16x32_bf16 v[138:141], v[6:9], v[110:113], v[138:141]
	v_mfma_f32_16x16x32_bf16 v[142:145], v[10:13], v[106:109], 0
	v_mfma_f32_16x16x32_bf16 v[152:155], v[6:9], v[118:121], v[152:155]
	v_mfma_f32_16x16x32_bf16 v[158:161], v[10:13], v[114:117], 0
	v_mfma_f32_16x16x32_bf16 v[2:5], v[6:9], v[126:129], v[2:5]
	v_mfma_f32_16x16x32_bf16 v[6:9], v[10:13], v[122:125], 0
	v_mfma_f32_16x16x32_bf16 v[134:137], v[14:17], v[102:105], v[134:137]
	v_mfma_f32_16x16x32_bf16 v[142:145], v[14:17], v[110:113], v[142:145]
	v_mfma_f32_16x16x32_bf16 v[158:161], v[14:17], v[118:121], v[158:161]
	v_mfma_f32_16x16x32_bf16 v[6:9], v[14:17], v[126:129], v[6:9]
	s_setprio 0
	s_setprio 1
	v_mfma_f32_16x16x32_bf16 v[10:13], v[18:21], v[62:65], 0
	v_mfma_f32_16x16x32_bf16 v[14:17], v[26:29], v[62:65], 0
	v_mfma_f32_16x16x32_bf16 v[10:13], v[22:25], v[102:105], v[10:13]
	v_mfma_f32_16x16x32_bf16 v[14:17], v[30:33], v[102:105], v[14:17]
	v_mfma_f32_16x16x32_bf16 v[62:65], v[18:21], v[106:109], 0
	v_mfma_f32_16x16x32_bf16 v[102:105], v[26:29], v[106:109], 0
	v_mfma_f32_16x16x32_bf16 v[106:109], v[18:21], v[114:117], 0
	v_mfma_f32_16x16x32_bf16 v[18:21], v[18:21], v[122:125], 0
	v_mfma_f32_16x16x32_bf16 v[62:65], v[22:25], v[110:113], v[62:65]
	v_mfma_f32_16x16x32_bf16 v[102:105], v[30:33], v[110:113], v[102:105]
	v_mfma_f32_16x16x32_bf16 v[106:109], v[22:25], v[118:121], v[106:109]
	v_mfma_f32_16x16x32_bf16 v[110:113], v[26:29], v[114:117], 0
	v_mfma_f32_16x16x32_bf16 v[18:21], v[22:25], v[126:129], v[18:21]
	v_mfma_f32_16x16x32_bf16 v[22:25], v[26:29], v[122:125], 0
	v_mfma_f32_16x16x32_bf16 v[110:113], v[30:33], v[118:121], v[110:113]
	v_mfma_f32_16x16x32_bf16 v[22:25], v[30:33], v[126:129], v[22:25]
	s_setprio 0
	s_barrier
	s_add_i32 s67, 0, 0x18000
	s_add_i32 s70, 0, 0x1c000
	v_add_u32_e32 v216, s67, v156
	v_add_u32_e32 v217, s70, v156
	ds_read_b128 v[26:29], v216
	ds_read_b128 v[30:33], v216 offset:1024
	ds_read_b128 v[114:117], v216 offset:2048
	ds_read_b128 v[118:121], v216 offset:3072
	ds_read_b128 v[122:125], v217
	ds_read_b128 v[126:129], v217 offset:1024
	ds_read_b128 v[162:165], v217 offset:2048
	ds_read_b128 v[166:169], v217 offset:3072
	s_add_u32 s68, s24, 0xb0100
	s_addc_u32 s69, s25, 0
	s_mov_b32 m0, s36
	v_lshl_add_u64 v[214:215], s[68:69], 0, v[150:151]
	ds_read_b128 v[170:173], v157 offset:32768
	ds_read_b128 v[174:177], v157 offset:33792
	ds_read_b128 v[178:181], v157 offset:34816
	ds_read_b128 v[182:185], v157 offset:35840
	ds_read_b128 v[190:193], v157 offset:36864
	ds_read_b128 v[194:197], v157 offset:37888
	ds_read_b128 v[198:201], v157 offset:38912
	ds_read_b128 v[202:205], v157 offset:39936
	global_load_lds_dwordx4 v[214:215], off
	v_lshl_add_u64 v[214:215], s[68:69], 0, v[148:149]
	s_mov_b32 m0, s37
	s_nop 0
	global_load_lds_dwordx4 v[214:215], off
	s_waitcnt vmcnt(8)
	s_waitcnt lgkmcnt(0)
	s_barrier
	s_setprio 1
	s_waitcnt lgkmcnt(0)
	v_mfma_f32_16x16x32_bf16 v[66:69], v[26:29], v[170:173], v[66:69]
	v_mfma_f32_16x16x32_bf16 v[70:73], v[114:117], v[170:173], v[70:73]
	v_mfma_f32_16x16x32_bf16 v[74:77], v[26:29], v[178:181], v[74:77]
	v_mfma_f32_16x16x32_bf16 v[78:81], v[114:117], v[178:181], v[78:81]
	v_mfma_f32_16x16x32_bf16 v[82:85], v[26:29], v[190:193], v[82:85]
	v_mfma_f32_16x16x32_bf16 v[86:89], v[114:117], v[190:193], v[86:89]
	v_mfma_f32_16x16x32_bf16 v[90:93], v[26:29], v[198:201], v[90:93]
	v_mfma_f32_16x16x32_bf16 v[94:97], v[114:117], v[198:201], v[94:97]
	v_mfma_f32_16x16x32_bf16 v[66:69], v[30:33], v[174:177], v[66:69]
	v_mfma_f32_16x16x32_bf16 v[70:73], v[118:121], v[174:177], v[70:73]
	v_mfma_f32_16x16x32_bf16 v[74:77], v[30:33], v[182:185], v[74:77]
	v_mfma_f32_16x16x32_bf16 v[78:81], v[118:121], v[182:185], v[78:81]
	v_mfma_f32_16x16x32_bf16 v[82:85], v[30:33], v[194:197], v[82:85]
	v_mfma_f32_16x16x32_bf16 v[86:89], v[118:121], v[194:197], v[86:89]
	v_mfma_f32_16x16x32_bf16 v[90:93], v[30:33], v[202:205], v[90:93]
	v_mfma_f32_16x16x32_bf16 v[94:97], v[118:121], v[202:205], v[94:97]
	s_setprio 0
	s_setprio 1
	v_mfma_f32_16x16x32_bf16 v[98:101], v[122:125], v[170:173], v[98:101]
	v_mfma_f32_16x16x32_bf16 v[34:37], v[162:165], v[170:173], v[34:37]
	v_mfma_f32_16x16x32_bf16 v[38:41], v[122:125], v[178:181], v[38:41]
	v_mfma_f32_16x16x32_bf16 v[42:45], v[162:165], v[178:181], v[42:45]
	v_mfma_f32_16x16x32_bf16 v[46:49], v[122:125], v[190:193], v[46:49]
	v_mfma_f32_16x16x32_bf16 v[50:53], v[162:165], v[190:193], v[50:53]
	v_mfma_f32_16x16x32_bf16 v[54:57], v[122:125], v[198:201], v[54:57]
	v_mfma_f32_16x16x32_bf16 v[58:61], v[162:165], v[198:201], v[58:61]
	v_mfma_f32_16x16x32_bf16 v[98:101], v[126:129], v[174:177], v[98:101]
	v_mfma_f32_16x16x32_bf16 v[34:37], v[166:169], v[174:177], v[34:37]
	v_mfma_f32_16x16x32_bf16 v[38:41], v[126:129], v[182:185], v[38:41]
	v_mfma_f32_16x16x32_bf16 v[42:45], v[166:169], v[182:185], v[42:45]
	v_mfma_f32_16x16x32_bf16 v[46:49], v[126:129], v[194:197], v[46:49]
	v_mfma_f32_16x16x32_bf16 v[50:53], v[166:169], v[194:197], v[50:53]
	v_mfma_f32_16x16x32_bf16 v[54:57], v[126:129], v[202:205], v[54:57]
	v_mfma_f32_16x16x32_bf16 v[58:61], v[166:169], v[202:205], v[58:61]
	s_setprio 0
	s_barrier
; #define PG8_STAGE(bufoff, gbase, voff) do { _Pragma("unroll") for (int _i = 0; _i < 2; ++_i) \
;         __builtin_amdgcn_global_load_lds((const unsigned*)((const char*)(gbase) + (voff)[_i]), (LAS unsigned*)(lds + (bufoff) + ldsw + _i * 8192), 16, 0, 0); } while (0)
; #define PG8_LDA(dst, b, h) do { _Pragma("unroll") for (int m = 0; m < 4; ++m) _Pragma("unroll") for (int k = 0; k < 2; ++k) dst[m][k] = *(const LAS bf16x8*)(lds + PG8_SA(b, h) + aoff + m * 2048 + k * 1024); } while (0)
; #define PG8_LDB(dst, b, h) do { _Pragma("unroll") for (int n = 0; n < 2; ++n) _Pragma("unroll") for (int k = 0; k < 2; ++k) dst[n][k] = *(const LAS bf16x8*)(lds + PG8_SB(b, h) + boff + n * 2048 + k * 1024); } while (0)
; #define PG8_MMA(ai, bj, At, Bt) do { __builtin_amdgcn_s_setprio(1); _Pragma("unroll") for (int m = 0; m < 4; ++m) _Pragma("unroll") for (int n = 0; n < 2; ++n) _Pragma("unroll") for (int k = 0; k < 2; ++k) \
;         acc[ai][bj][m][n] = __builtin_amdgcn_mfma_f32_16x16x32_bf16(Bt[n][k], At[m][k], acc[ai][bj][m][n], 0, 0, 0); __builtin_amdgcn_s_setprio(0); } while (0)
; #define PG8_WAIT_V(n) asm volatile("s_waitcnt vmcnt(" #n ")" ::: "memory")
; #define PG8_WAIT_L(n) asm volatile("s_waitcnt lgkmcnt(" #n ")" ::: "memory")
; #define PG8_BAR __builtin_amdgcn_s_barrier()
;     ...
;             if constexpr (SP2) {
;             PG8_LDB(B0, 0, 0); PG8_LDB(B1, 0, 1); PG8_SCHED; PG8_LDA(At, 0, 0); PG8_STAGE(PG8_SA(1, 1), a1 + hstepA, voffA);
;             PG8_WAIT_V(8); PG8_WAIT_L(0); PG8_BAR; PG8_MMA(0, 0, At, B0); PG8_MMA(0, 1, At, B1); PG8_BAR; PG8_SCHED;
;             PG8_LDA(At, 0, 1); PG8_STAGE(PG8_SB(0, 0), b2, voffB); PG8_STAGE(PG8_SB(0, 1), b2 + hstepB, voffB); PG8_STAGE(PG8_SA(0, 0), a2, voffA);
;             PG8_WAIT_V(8); PG8_WAIT_L(0); PG8_BAR; PG8_MMA(1, 0, At, B0); PG8_MMA(1, 1, At, B1); PG8_BAR; PG8_SCHED;
;             PG8_LDB(B0, 1, 0); PG8_LDB(B1, 1, 1); PG8_SCHED; PG8_LDA(At, 1, 0); PG8_STAGE(PG8_SA(0, 1), a2 + hstepA, voffA);
;             PG8_WAIT_V(8); PG8_WAIT_L(0); PG8_BAR; PG8_MMA(0, 0, At, B0); PG8_MMA(0, 1, At, B1); PG8_BAR; PG8_SCHED;
;             PG8_LDA(At, 1, 1); PG8_STAGE(PG8_SB(1, 0), b3, voffB); PG8_STAGE(PG8_SB(1, 1), b3 + hstepB, voffB); PG8_STAGE(PG8_SA(1, 0), a3, voffA);
;             PG8_WAIT_V(8); PG8_WAIT_L(0); PG8_BAR; PG8_MMA(1, 0, At, B0); PG8_MMA(1, 1, At, B1); PG8_BAR; PG8_SCHED;
	s_add_i32 s67, s67, s33
	s_mov_b64 s[90:91], 0x180
	s_add_i32 s65, s67, 0x2000
	v_lshl_add_u64 v[206:207], v[206:207], 0, s[90:91]
	s_mov_b32 m0, s67
	s_add_u32 s68, s26, 0x10180
	ds_read_b128 v[170:173], v157 offset:49152
	ds_read_b128 v[174:177], v157 offset:50176
	ds_read_b128 v[178:181], v157 offset:51200
	ds_read_b128 v[182:185], v157 offset:52224
	ds_read_b128 v[190:193], v157 offset:53248
	ds_read_b128 v[194:197], v157 offset:54272
	ds_read_b128 v[198:201], v157 offset:55296
	ds_read_b128 v[202:205], v157 offset:56320
	global_load_lds_dwordx4 v[206:207], off
	v_lshl_add_u64 v[206:207], v[208:209], 0, s[90:91]
	s_mov_b32 m0, s65
	s_addc_u32 s69, s27, 0
	s_add_i32 s26, s70, s33
	global_load_lds_dwordx4 v[206:207], off
	v_lshl_add_u64 v[206:207], s[68:69], 0, v[186:187]
	s_mov_b32 m0, s26
	s_add_i32 s27, s26, 0x2000
	global_load_lds_dwordx4 v[206:207], off
	v_lshl_add_u64 v[206:207], s[68:69], 0, v[146:147]
	s_mov_b32 m0, s27
	s_nop 0
	global_load_lds_dwordx4 v[206:207], off
	v_lshl_add_u64 v[206:207], v[210:211], 0, s[90:91]
	s_mov_b32 m0, s50
	s_nop 0
	global_load_lds_dwordx4 v[206:207], off
	v_lshl_add_u64 v[206:207], v[212:213], 0, s[90:91]
	s_mov_b32 m0, s51
	s_nop 0
	global_load_lds_dwordx4 v[206:207], off
	s_waitcnt vmcnt(8)
	s_waitcnt lgkmcnt(0)
	s_barrier
	s_setprio 1
	s_waitcnt lgkmcnt(0)
	v_mfma_f32_16x16x32_bf16 v[130:133], v[26:29], v[170:173], v[130:133]
	v_mfma_f32_16x16x32_bf16 v[134:137], v[114:117], v[170:173], v[134:137]
	v_mfma_f32_16x16x32_bf16 v[138:141], v[26:29], v[178:181], v[138:141]
	v_mfma_f32_16x16x32_bf16 v[142:145], v[114:117], v[178:181], v[142:145]
	v_mfma_f32_16x16x32_bf16 v[152:155], v[26:29], v[190:193], v[152:155]
	v_mfma_f32_16x16x32_bf16 v[158:161], v[114:117], v[190:193], v[158:161]
	v_mfma_f32_16x16x32_bf16 v[2:5], v[26:29], v[198:201], v[2:5]
	v_mfma_f32_16x16x32_bf16 v[6:9], v[114:117], v[198:201], v[6:9]
	v_mfma_f32_16x16x32_bf16 v[130:133], v[30:33], v[174:177], v[130:133]
	v_mfma_f32_16x16x32_bf16 v[134:137], v[118:121], v[174:177], v[134:137]
	v_mfma_f32_16x16x32_bf16 v[138:141], v[30:33], v[182:185], v[138:141]
	v_mfma_f32_16x16x32_bf16 v[142:145], v[118:121], v[182:185], v[142:145]
	v_mfma_f32_16x16x32_bf16 v[152:155], v[30:33], v[194:197], v[152:155]
	v_mfma_f32_16x16x32_bf16 v[158:161], v[118:121], v[194:197], v[158:161]
	v_mfma_f32_16x16x32_bf16 v[2:5], v[30:33], v[202:205], v[2:5]
	v_mfma_f32_16x16x32_bf16 v[6:9], v[118:121], v[202:205], v[6:9]
	s_setprio 0
	s_setprio 1
	v_mfma_f32_16x16x32_bf16 v[10:13], v[122:125], v[170:173], v[10:13]
	v_mfma_f32_16x16x32_bf16 v[14:17], v[162:165], v[170:173], v[14:17]
	v_mfma_f32_16x16x32_bf16 v[26:29], v[122:125], v[178:181], v[62:65]
	v_mfma_f32_16x16x32_bf16 v[30:33], v[162:165], v[178:181], v[102:105]
	v_mfma_f32_16x16x32_bf16 v[62:65], v[122:125], v[190:193], v[106:109]
	v_mfma_f32_16x16x32_bf16 v[102:105], v[162:165], v[190:193], v[110:113]
	v_mfma_f32_16x16x32_bf16 v[18:21], v[122:125], v[198:201], v[18:21]
	v_mfma_f32_16x16x32_bf16 v[22:25], v[162:165], v[198:201], v[22:25]
	v_mfma_f32_16x16x32_bf16 v[10:13], v[126:129], v[174:177], v[10:13]
	v_mfma_f32_16x16x32_bf16 v[14:17], v[166:169], v[174:177], v[14:17]
	v_mfma_f32_16x16x32_bf16 v[26:29], v[126:129], v[182:185], v[26:29]
	v_mfma_f32_16x16x32_bf16 v[30:33], v[166:169], v[182:185], v[30:33]
	v_mfma_f32_16x16x32_bf16 v[62:65], v[126:129], v[194:197], v[62:65]
	v_mfma_f32_16x16x32_bf16 v[102:105], v[166:169], v[194:197], v[102:105]
	v_mfma_f32_16x16x32_bf16 v[18:21], v[126:129], v[202:205], v[18:21]
	v_mfma_f32_16x16x32_bf16 v[22:25], v[166:169], v[202:205], v[22:25]
	s_setprio 0
	s_barrier
	ds_read_b128 v[106:109], v188
	ds_read_b128 v[110:113], v188 offset:1024
	ds_read_b128 v[114:117], v188 offset:2048
	ds_read_b128 v[118:121], v188 offset:3072
	ds_read_b128 v[122:125], v189
	ds_read_b128 v[126:129], v189 offset:1024
	ds_read_b128 v[162:165], v189 offset:2048
	ds_read_b128 v[166:169], v189 offset:3072
	s_add_u32 s24, s24, 0xb0180
	s_addc_u32 s25, s25, 0
	s_mov_b32 m0, s66
	v_lshl_add_u64 v[206:207], s[24:25], 0, v[150:151]
	ds_read_b128 v[170:173], v157
	ds_read_b128 v[174:177], v157 offset:1024
	ds_read_b128 v[178:181], v157 offset:2048
	ds_read_b128 v[182:185], v157 offset:3072
	ds_read_b128 v[190:193], v157 offset:4096
	ds_read_b128 v[194:197], v157 offset:5120
	ds_read_b128 v[198:201], v157 offset:6144
	ds_read_b128 v[202:205], v157 offset:7168
	global_load_lds_dwordx4 v[206:207], off
	v_lshl_add_u64 v[206:207], s[24:25], 0, v[148:149]
	s_mov_b32 m0, s19
	s_nop 0
	global_load_lds_dwordx4 v[206:207], off
	s_waitcnt vmcnt(8)
	s_waitcnt lgkmcnt(0)
	s_barrier
; #define PG8_STAGE(bufoff, gbase, voff) do { _Pragma("unroll") for (int _i = 0; _i < 2; ++_i) \
;         __builtin_amdgcn_global_load_lds((const unsigned*)((const char*)(gbase) + (voff)[_i]), (LAS unsigned*)(lds + (bufoff) + ldsw + _i * 8192), 16, 0, 0); } while (0)
; #define PG8_LDA(dst, b, h) do { _Pragma("unroll") for (int m = 0; m < 4; ++m) _Pragma("unroll") for (int k = 0; k < 2; ++k) dst[m][k] = *(const LAS bf16x8*)(lds + PG8_SA(b, h) + aoff + m * 2048 + k * 1024); } while (0)
; #define PG8_LDB(dst, b, h) do { _Pragma("unroll") for (int n = 0; n < 2; ++n) _Pragma("unroll") for (int k = 0; k < 2; ++k) dst[n][k] = *(const LAS bf16x8*)(lds + PG8_SB(b, h) + boff + n * 2048 + k * 1024); } while (0)
; #define PG8_MMA(ai, bj, At, Bt) do { __builtin_amdgcn_s_setprio(1); _Pragma("unroll") for (int m = 0; m < 4; ++m) _Pragma("unroll") for (int n = 0; n < 2; ++n) _Pragma("unroll") for (int k = 0; k < 2; ++k) \
;         acc[ai][bj][m][n] = __builtin_amdgcn_mfma_f32_16x16x32_bf16(Bt[n][k], At[m][k], acc[ai][bj][m][n], 0, 0, 0); __builtin_amdgcn_s_setprio(0); } while (0)
; #define PG8_WAIT_V(n) asm volatile("s_waitcnt vmcnt(" #n ")" ::: "memory")
; #define PG8_WAIT_L(n) asm volatile("s_waitcnt lgkmcnt(" #n ")" ::: "memory")
; #define PG8_BAR __builtin_amdgcn_s_barrier()
;     ...
;             if constexpr (SP2) {
;             PG8_LDB(B0, 0, 0); PG8_LDB(B1, 0, 1); PG8_SCHED; PG8_LDA(At, 0, 0); PG8_STAGE(PG8_SA(1, 1), a1 + hstepA, voffA);
;             PG8_WAIT_V(8); PG8_WAIT_L(0); PG8_BAR; PG8_MMA(0, 0, At, B0); PG8_MMA(0, 1, At, B1); PG8_BAR; PG8_SCHED;
;             PG8_LDA(At, 0, 1); PG8_STAGE(PG8_SB(0, 0), b2, voffB); PG8_STAGE(PG8_SB(0, 1), b2 + hstepB, voffB); PG8_STAGE(PG8_SA(0, 0), a2, voffA);
;             PG8_WAIT_V(8); PG8_WAIT_L(0); PG8_BAR; PG8_MMA(1, 0, At, B0); PG8_MMA(1, 1, At, B1); PG8_BAR; PG8_SCHED;
;             PG8_LDB(B0, 1, 0); PG8_LDB(B1, 1, 1); PG8_SCHED; PG8_LDA(At, 1, 0); PG8_STAGE(PG8_SA(0, 1), a2 + hstepA, voffA);
;             PG8_WAIT_V(8); PG8_WAIT_L(0); PG8_BAR; PG8_MMA(0, 0, At, B0); PG8_MMA(0, 1, At, B1); PG8_BAR; PG8_SCHED;
;             PG8_LDA(At, 1, 1); PG8_STAGE(PG8_SB(1, 0), b3, voffB); PG8_STAGE(PG8_SB(1, 1), b3 + hstepB, voffB); PG8_STAGE(PG8_SA(1, 0), a3, voffA);
;             PG8_WAIT_V(8); PG8_WAIT_L(0); PG8_BAR; PG8_MMA(1, 0, At, B0); PG8_MMA(1, 1, At, B1); PG8_BAR; PG8_SCHED;
	s_setprio 1
	s_waitcnt lgkmcnt(0)
	v_mfma_f32_16x16x32_bf16 v[90:93], v[106:109], v[198:201], v[90:93]
	v_mfma_f32_16x16x32_bf16 v[66:69], v[106:109], v[170:173], v[66:69]
	v_mfma_f32_16x16x32_bf16 v[70:73], v[114:117], v[170:173], v[70:73]
	v_mfma_f32_16x16x32_bf16 v[74:77], v[106:109], v[178:181], v[74:77]
	v_mfma_f32_16x16x32_bf16 v[78:81], v[114:117], v[178:181], v[78:81]
	v_mfma_f32_16x16x32_bf16 v[82:85], v[106:109], v[190:193], v[82:85]
	v_mfma_f32_16x16x32_bf16 v[86:89], v[114:117], v[190:193], v[86:89]
	v_mfma_f32_16x16x32_bf16 v[206:209], v[110:113], v[202:205], v[90:93]
	v_mfma_f32_16x16x32_bf16 v[90:93], v[114:117], v[198:201], v[94:97]
	v_mfma_f32_16x16x32_bf16 v[66:69], v[110:113], v[174:177], v[66:69]
	v_mfma_f32_16x16x32_bf16 v[70:73], v[118:121], v[174:177], v[70:73]
	v_mfma_f32_16x16x32_bf16 v[74:77], v[110:113], v[182:185], v[74:77]
	v_mfma_f32_16x16x32_bf16 v[78:81], v[118:121], v[182:185], v[78:81]
	v_mfma_f32_16x16x32_bf16 v[82:85], v[110:113], v[194:197], v[82:85]
	v_mfma_f32_16x16x32_bf16 v[86:89], v[118:121], v[194:197], v[86:89]
	v_mfma_f32_16x16x32_bf16 v[94:97], v[118:121], v[202:205], v[90:93]
	s_setprio 0
	s_setprio 1
	v_mfma_f32_16x16x32_bf16 v[90:93], v[122:125], v[170:173], v[98:101]
	v_mfma_f32_16x16x32_bf16 v[34:37], v[162:165], v[170:173], v[34:37]
	v_mfma_f32_16x16x32_bf16 v[38:41], v[122:125], v[178:181], v[38:41]
	v_mfma_f32_16x16x32_bf16 v[42:45], v[162:165], v[178:181], v[42:45]
	v_mfma_f32_16x16x32_bf16 v[46:49], v[122:125], v[190:193], v[46:49]
	v_mfma_f32_16x16x32_bf16 v[50:53], v[162:165], v[190:193], v[50:53]
	v_mfma_f32_16x16x32_bf16 v[54:57], v[122:125], v[198:201], v[54:57]
	v_mfma_f32_16x16x32_bf16 v[58:61], v[162:165], v[198:201], v[58:61]
	v_mfma_f32_16x16x32_bf16 v[210:213], v[126:129], v[174:177], v[90:93]
	v_mfma_f32_16x16x32_bf16 v[34:37], v[166:169], v[174:177], v[34:37]
	v_mfma_f32_16x16x32_bf16 v[38:41], v[126:129], v[182:185], v[38:41]
	v_mfma_f32_16x16x32_bf16 v[42:45], v[166:169], v[182:185], v[42:45]
	v_mfma_f32_16x16x32_bf16 v[46:49], v[126:129], v[194:197], v[46:49]
	v_mfma_f32_16x16x32_bf16 v[50:53], v[166:169], v[194:197], v[50:53]
	v_mfma_f32_16x16x32_bf16 v[54:57], v[126:129], v[202:205], v[54:57]
	v_mfma_f32_16x16x32_bf16 v[58:61], v[166:169], v[202:205], v[58:61]
	s_setprio 0
	s_barrier
	s_mov_b32 m0, s57
	v_lshl_add_u64 v[246:247], s[0:1], 0, v[186:187]
	s_add_u32 s24, s0, 0x10000
	ds_read_b128 v[90:93], v157 offset:16384
	ds_read_b128 v[98:101], v157 offset:17408
	ds_read_b128 v[170:173], v157 offset:18432
	ds_read_b128 v[174:177], v157 offset:19456
	ds_read_b128 v[178:181], v157 offset:20480
	ds_read_b128 v[182:185], v157 offset:21504
	ds_read_b128 v[190:193], v157 offset:22528
	ds_read_b128 v[194:197], v157 offset:23552
	global_load_lds_dwordx4 v[246:247], off
	v_lshl_add_u64 v[248:249], s[0:1], 0, v[146:147]
	s_mov_b32 m0, s53
	s_addc_u32 s25, s1, 0
	global_load_lds_dwordx4 v[248:249], off
	v_lshl_add_u64 v[198:199], s[24:25], 0, v[186:187]
	s_mov_b32 m0, s54
	v_lshl_add_u64 v[250:251], s[20:21], 0, v[150:151]
	global_load_lds_dwordx4 v[198:199], off
	v_lshl_add_u64 v[198:199], s[24:25], 0, v[146:147]
	s_mov_b32 m0, s55
	v_lshl_add_u64 v[252:253], s[20:21], 0, v[148:149]
	global_load_lds_dwordx4 v[198:199], off
	s_mov_b32 m0, s34
	s_nop 0
	global_load_lds_dwordx4 v[250:251], off
	s_mov_b32 m0, s35
	s_nop 0
	global_load_lds_dwordx4 v[252:253], off
	s_waitcnt vmcnt(8)
	s_waitcnt lgkmcnt(0)
	s_barrier
	s_setprio 1
	s_waitcnt lgkmcnt(0)
	v_mfma_f32_16x16x32_bf16 v[130:133], v[106:109], v[90:93], v[130:133]
	v_mfma_f32_16x16x32_bf16 v[134:137], v[114:117], v[90:93], v[134:137]
	v_mfma_f32_16x16x32_bf16 v[138:141], v[106:109], v[170:173], v[138:141]
	v_mfma_f32_16x16x32_bf16 v[142:145], v[114:117], v[170:173], v[142:145]
	v_mfma_f32_16x16x32_bf16 v[152:155], v[106:109], v[178:181], v[152:155]
	v_mfma_f32_16x16x32_bf16 v[158:161], v[114:117], v[178:181], v[158:161]
	v_mfma_f32_16x16x32_bf16 v[2:5], v[106:109], v[190:193], v[2:5]
	v_mfma_f32_16x16x32_bf16 v[6:9], v[114:117], v[190:193], v[6:9]
	v_mfma_f32_16x16x32_bf16 v[130:133], v[110:113], v[98:101], v[130:133]
	v_mfma_f32_16x16x32_bf16 v[134:137], v[118:121], v[98:101], v[134:137]
	v_mfma_f32_16x16x32_bf16 v[138:141], v[110:113], v[174:177], v[138:141]
	v_mfma_f32_16x16x32_bf16 v[142:145], v[118:121], v[174:177], v[142:145]
	v_mfma_f32_16x16x32_bf16 v[152:155], v[110:113], v[182:185], v[152:155]
	v_mfma_f32_16x16x32_bf16 v[158:161], v[118:121], v[182:185], v[158:161]
	v_mfma_f32_16x16x32_bf16 v[2:5], v[110:113], v[194:197], v[2:5]
	v_mfma_f32_16x16x32_bf16 v[6:9], v[118:121], v[194:197], v[6:9]
	s_setprio 0
	s_setprio 1
	v_mfma_f32_16x16x32_bf16 v[10:13], v[122:125], v[90:93], v[10:13]
	v_mfma_f32_16x16x32_bf16 v[198:201], v[126:129], v[98:101], v[10:13]
	v_mfma_f32_16x16x32_bf16 v[10:13], v[162:165], v[90:93], v[14:17]
	v_mfma_f32_16x16x32_bf16 v[14:17], v[166:169], v[98:101], v[10:13]
	v_mfma_f32_16x16x32_bf16 v[10:13], v[122:125], v[170:173], v[26:29]
	v_mfma_f32_16x16x32_bf16 v[202:205], v[126:129], v[174:177], v[10:13]
	v_mfma_f32_16x16x32_bf16 v[10:13], v[162:165], v[170:173], v[30:33]
	v_mfma_f32_16x16x32_bf16 v[30:33], v[166:169], v[174:177], v[10:13]
	v_mfma_f32_16x16x32_bf16 v[10:13], v[122:125], v[178:181], v[62:65]
	v_mfma_f32_16x16x32_bf16 v[170:173], v[126:129], v[182:185], v[10:13]
	v_mfma_f32_16x16x32_bf16 v[10:13], v[162:165], v[178:181], v[102:105]
	v_mfma_f32_16x16x32_bf16 v[174:177], v[166:169], v[182:185], v[10:13]
	v_mfma_f32_16x16x32_bf16 v[10:13], v[122:125], v[190:193], v[18:21]
	v_mfma_f32_16x16x32_bf16 v[178:181], v[126:129], v[194:197], v[10:13]
	v_mfma_f32_16x16x32_bf16 v[10:13], v[162:165], v[190:193], v[22:25]
	v_mfma_f32_16x16x32_bf16 v[162:165], v[166:169], v[194:197], v[10:13]
	s_setprio 0
	s_barrier
; #define PG8_STAGE(bufoff, gbase, voff) do { _Pragma("unroll") for (int _i = 0; _i < 2; ++_i) \
;         __builtin_amdgcn_global_load_lds((const unsigned*)((const char*)(gbase) + (voff)[_i]), (LAS unsigned*)(lds + (bufoff) + ldsw + _i * 8192), 16, 0, 0); } while (0)
; #define PG8_LDA(dst, b, h) do { _Pragma("unroll") for (int m = 0; m < 4; ++m) _Pragma("unroll") for (int k = 0; k < 2; ++k) dst[m][k] = *(const LAS bf16x8*)(lds + PG8_SA(b, h) + aoff + m * 2048 + k * 1024); } while (0)
; #define PG8_LDB(dst, b, h) do { _Pragma("unroll") for (int n = 0; n < 2; ++n) _Pragma("unroll") for (int k = 0; k < 2; ++k) dst[n][k] = *(const LAS bf16x8*)(lds + PG8_SB(b, h) + boff + n * 2048 + k * 1024); } while (0)
; #define PG8_MMA(ai, bj, At, Bt) do { __builtin_amdgcn_s_setprio(1); _Pragma("unroll") for (int m = 0; m < 4; ++m) _Pragma("unroll") for (int n = 0; n < 2; ++n) _Pragma("unroll") for (int k = 0; k < 2; ++k) \
;         acc[ai][bj][m][n] = __builtin_amdgcn_mfma_f32_16x16x32_bf16(Bt[n][k], At[m][k], acc[ai][bj][m][n], 0, 0, 0); __builtin_amdgcn_s_setprio(0); } while (0)
; #define PG8_WAIT_V(n) asm volatile("s_waitcnt vmcnt(" #n ")" ::: "memory")
; #define PG8_WAIT_L(n) asm volatile("s_waitcnt lgkmcnt(" #n ")" ::: "memory")
; #define PG8_BAR __builtin_amdgcn_s_barrier()
;     ...
;             if constexpr (SP2) {
;             PG8_LDB(B0, 0, 0); PG8_LDB(B1, 0, 1); PG8_SCHED; PG8_LDA(At, 0, 0); PG8_STAGE(PG8_SA(1, 1), a1 + hstepA, voffA);
;             PG8_WAIT_V(8); PG8_WAIT_L(0); PG8_BAR; PG8_MMA(0, 0, At, B0); PG8_MMA(0, 1, At, B1); PG8_BAR; PG8_SCHED;
;             PG8_LDA(At, 0, 1); PG8_STAGE(PG8_SB(0, 0), b2, voffB); PG8_STAGE(PG8_SB(0, 1), b2 + hstepB, voffB); PG8_STAGE(PG8_SA(0, 0), a2, voffA);
;             PG8_WAIT_V(8); PG8_WAIT_L(0); PG8_BAR; PG8_MMA(1, 0, At, B0); PG8_MMA(1, 1, At, B1); PG8_BAR; PG8_SCHED;
;             PG8_LDB(B0, 1, 0); PG8_LDB(B1, 1, 1); PG8_SCHED; PG8_LDA(At, 1, 0); PG8_STAGE(PG8_SA(0, 1), a2 + hstepA, voffA);
;             PG8_WAIT_V(8); PG8_WAIT_L(0); PG8_BAR; PG8_MMA(0, 0, At, B0); PG8_MMA(0, 1, At, B1); PG8_BAR; PG8_SCHED;
;             PG8_LDA(At, 1, 1); PG8_STAGE(PG8_SB(1, 0), b3, voffB); PG8_STAGE(PG8_SB(1, 1), b3 + hstepB, voffB); PG8_STAGE(PG8_SA(1, 0), a3, voffA);
;             PG8_WAIT_V(8); PG8_WAIT_L(0); PG8_BAR; PG8_MMA(1, 0, At, B0); PG8_MMA(1, 1, At, B1); PG8_BAR; PG8_SCHED;
	s_nop 4
	ds_read_b128 v[10:13], v216
	ds_read_b128 v[22:25], v216 offset:1024
	ds_read_b128 v[62:65], v216 offset:2048
	ds_read_b128 v[166:169], v216 offset:3072
	ds_read_b128 v[182:185], v217
	ds_read_b128 v[190:193], v217 offset:1024
	ds_read_b128 v[194:197], v217 offset:2048
	ds_read_b128 v[214:217], v217 offset:3072
	s_add_u32 s24, s20, 0xb0000
	s_addc_u32 s25, s21, 0
	s_mov_b32 m0, s36
	v_lshl_add_u64 v[90:91], s[24:25], 0, v[150:151]
	ds_read_b128 v[18:21], v157 offset:32768
	ds_read_b128 v[26:29], v157 offset:33792
	ds_read_b128 v[102:105], v157 offset:34816
	ds_read_b128 v[218:221], v157 offset:35840
	ds_read_b128 v[222:225], v157 offset:36864
	ds_read_b128 v[226:229], v157 offset:37888
	ds_read_b128 v[230:233], v157 offset:38912
	ds_read_b128 v[234:237], v157 offset:39936
	global_load_lds_dwordx4 v[90:91], off
	v_lshl_add_u64 v[90:91], s[24:25], 0, v[148:149]
	s_mov_b32 m0, s37
	s_nop 0
	global_load_lds_dwordx4 v[90:91], off
	s_waitcnt vmcnt(8)
	s_waitcnt lgkmcnt(0)
	s_barrier
	s_setprio 1
	s_waitcnt lgkmcnt(0)
	v_mfma_f32_16x16x32_bf16 v[66:69], v[10:13], v[18:21], v[66:69]
	v_mfma_f32_16x16x32_bf16 v[122:125], v[22:25], v[26:29], v[66:69]
	v_mfma_f32_16x16x32_bf16 v[66:69], v[62:65], v[18:21], v[70:73]
	v_mfma_f32_16x16x32_bf16 v[114:117], v[166:169], v[26:29], v[66:69]
	v_mfma_f32_16x16x32_bf16 v[66:69], v[10:13], v[102:105], v[74:77]
	v_mfma_f32_16x16x32_bf16 v[106:109], v[22:25], v[218:221], v[66:69]
	v_mfma_f32_16x16x32_bf16 v[66:69], v[62:65], v[102:105], v[78:81]
	v_mfma_f32_16x16x32_bf16 v[98:101], v[166:169], v[218:221], v[66:69]
	v_mfma_f32_16x16x32_bf16 v[66:69], v[10:13], v[222:225], v[82:85]
	v_mfma_f32_16x16x32_bf16 v[90:93], v[22:25], v[226:229], v[66:69]
	v_mfma_f32_16x16x32_bf16 v[66:69], v[62:65], v[222:225], v[86:89]
	v_mfma_f32_16x16x32_bf16 v[82:85], v[166:169], v[226:229], v[66:69]
	v_mfma_f32_16x16x32_bf16 v[66:69], v[10:13], v[230:233], v[206:209]
	v_mfma_f32_16x16x32_bf16 v[74:77], v[22:25], v[234:237], v[66:69]
	v_mfma_f32_16x16x32_bf16 v[66:69], v[62:65], v[230:233], v[94:97]
	v_mfma_f32_16x16x32_bf16 v[66:69], v[166:169], v[234:237], v[66:69]
	s_setprio 0
	s_setprio 1
	v_mfma_f32_16x16x32_bf16 v[70:73], v[182:185], v[18:21], v[210:213]
	v_mfma_f32_16x16x32_bf16 v[18:21], v[194:197], v[18:21], v[34:37]
	v_mfma_f32_16x16x32_bf16 v[118:121], v[214:217], v[26:29], v[18:21]
	v_mfma_f32_16x16x32_bf16 v[18:21], v[182:185], v[102:105], v[38:41]
	v_mfma_f32_16x16x32_bf16 v[110:113], v[190:193], v[218:221], v[18:21]
	v_mfma_f32_16x16x32_bf16 v[18:21], v[194:197], v[102:105], v[42:45]
	v_mfma_f32_16x16x32_bf16 v[102:105], v[214:217], v[218:221], v[18:21]
	v_mfma_f32_16x16x32_bf16 v[18:21], v[182:185], v[222:225], v[46:49]
	v_mfma_f32_16x16x32_bf16 v[94:97], v[190:193], v[226:229], v[18:21]
	v_mfma_f32_16x16x32_bf16 v[18:21], v[194:197], v[222:225], v[50:53]
	v_mfma_f32_16x16x32_bf16 v[86:89], v[214:217], v[226:229], v[18:21]
	v_mfma_f32_16x16x32_bf16 v[18:21], v[182:185], v[230:233], v[54:57]
	v_mfma_f32_16x16x32_bf16 v[78:81], v[190:193], v[234:237], v[18:21]
	v_mfma_f32_16x16x32_bf16 v[18:21], v[194:197], v[230:233], v[58:61]
	v_mfma_f32_16x16x32_bf16 v[126:129], v[190:193], v[26:29], v[70:73]
	v_mfma_f32_16x16x32_bf16 v[70:73], v[214:217], v[234:237], v[18:21]
	s_setprio 0
	s_barrier
	s_mov_b32 m0, s67
	s_nop 2
	v_lshl_add_u64 v[18:19], v[246:247], 0, s[12:13]
	s_add_u32 s0, s0, 0x10080
	ds_read_b128 v[38:41], v157 offset:49152
	ds_read_b128 v[46:49], v157 offset:50176
	ds_read_b128 v[206:209], v157 offset:51200
	ds_read_b128 v[210:213], v157 offset:52224
	ds_read_b128 v[218:221], v157 offset:53248
	ds_read_b128 v[222:225], v157 offset:54272
	ds_read_b128 v[226:229], v157 offset:55296
	ds_read_b128 v[230:233], v157 offset:56320
	global_load_lds_dwordx4 v[18:19], off
	v_lshl_add_u64 v[18:19], v[248:249], 0, s[12:13]
	s_mov_b32 m0, s65
	s_addc_u32 s1, s1, 0
	global_load_lds_dwordx4 v[18:19], off
	v_lshl_add_u64 v[18:19], s[0:1], 0, v[186:187]
	s_mov_b32 m0, s26
	s_nop 0
	global_load_lds_dwordx4 v[18:19], off
	v_lshl_add_u64 v[18:19], s[0:1], 0, v[146:147]
	s_mov_b32 m0, s27
	s_nop 0
	global_load_lds_dwordx4 v[18:19], off
	v_lshl_add_u64 v[18:19], v[250:251], 0, s[12:13]
	s_mov_b32 m0, s50
	s_nop 0
	global_load_lds_dwordx4 v[18:19], off
	v_lshl_add_u64 v[18:19], v[252:253], 0, s[12:13]
	s_mov_b32 m0, s51
	s_nop 0
	global_load_lds_dwordx4 v[18:19], off
	s_waitcnt vmcnt(8)
	s_waitcnt lgkmcnt(0)
	s_barrier
	s_setprio 1
	s_waitcnt lgkmcnt(0)
	v_mfma_f32_16x16x32_bf16 v[18:21], v[10:13], v[38:41], v[130:133]
	v_mfma_f32_16x16x32_bf16 v[58:61], v[22:25], v[46:49], v[18:21]
	v_mfma_f32_16x16x32_bf16 v[18:21], v[62:65], v[38:41], v[134:137]
	v_mfma_f32_16x16x32_bf16 v[50:53], v[166:169], v[46:49], v[18:21]
	v_mfma_f32_16x16x32_bf16 v[18:21], v[10:13], v[206:209], v[138:141]
	v_mfma_f32_16x16x32_bf16 v[42:45], v[22:25], v[210:213], v[18:21]
	v_mfma_f32_16x16x32_bf16 v[18:21], v[62:65], v[206:209], v[142:145]
	v_mfma_f32_16x16x32_bf16 v[34:37], v[166:169], v[210:213], v[18:21]
	v_mfma_f32_16x16x32_bf16 v[18:21], v[10:13], v[218:221], v[152:155]
	v_mfma_f32_16x16x32_bf16 v[2:5], v[10:13], v[226:229], v[2:5]
	v_mfma_f32_16x16x32_bf16 v[26:29], v[22:25], v[222:225], v[18:21]
	v_mfma_f32_16x16x32_bf16 v[18:21], v[62:65], v[218:221], v[158:161]
	v_mfma_f32_16x16x32_bf16 v[10:13], v[22:25], v[230:233], v[2:5]
	v_mfma_f32_16x16x32_bf16 v[2:5], v[62:65], v[226:229], v[6:9]
	v_mfma_f32_16x16x32_bf16 v[18:21], v[166:169], v[222:225], v[18:21]
	v_mfma_f32_16x16x32_bf16 v[2:5], v[166:169], v[230:233], v[2:5]
	s_setprio 0
	s_setprio 1
	v_mfma_f32_16x16x32_bf16 v[6:9], v[182:185], v[38:41], v[198:201]
	v_mfma_f32_16x16x32_bf16 v[62:65], v[190:193], v[46:49], v[6:9]
	v_mfma_f32_16x16x32_bf16 v[6:9], v[194:197], v[38:41], v[14:17]
	v_mfma_f32_16x16x32_bf16 v[54:57], v[214:217], v[46:49], v[6:9]
	v_mfma_f32_16x16x32_bf16 v[6:9], v[182:185], v[206:209], v[202:205]
	v_mfma_f32_16x16x32_bf16 v[46:49], v[190:193], v[210:213], v[6:9]
	v_mfma_f32_16x16x32_bf16 v[6:9], v[194:197], v[206:209], v[30:33]
	v_mfma_f32_16x16x32_bf16 v[38:41], v[214:217], v[210:213], v[6:9]
	v_mfma_f32_16x16x32_bf16 v[6:9], v[182:185], v[218:221], v[170:173]
	v_mfma_f32_16x16x32_bf16 v[30:33], v[190:193], v[222:225], v[6:9]
	v_mfma_f32_16x16x32_bf16 v[6:9], v[194:197], v[218:221], v[174:177]
	v_mfma_f32_16x16x32_bf16 v[22:25], v[214:217], v[222:225], v[6:9]
	v_mfma_f32_16x16x32_bf16 v[6:9], v[182:185], v[226:229], v[178:181]
	v_mfma_f32_16x16x32_bf16 v[14:17], v[190:193], v[230:233], v[6:9]
	v_mfma_f32_16x16x32_bf16 v[6:9], v[194:197], v[226:229], v[162:165]
	v_mfma_f32_16x16x32_bf16 v[6:9], v[214:217], v[230:233], v[6:9]
	s_setprio 0
	s_barrier
; __device__ __forceinline__ unsigned pk2(float lo, float hi) { return f2bf(lo) | (f2bf(hi) << 16); }
; #define GATES_UCLOAD(buf, am_) do { _Pragma("unroll") for (int mm = 0; mm < 2; ++mm) ucw[buf][mm] = *(const u32x4*)(UC + (size_t)(row0 + ((am_) >> 1) * HALF + (((am_) & 1) * 2 + mm) * 16) * LW + ch0); } while (0)
;     __device__ __forceinline__ void operator()(const f32x4 (&acc)[2][2][4][2], const Unit& u, int wr, int wc, int fr, int fq) const {
;         const int blk = u.pn >> 2, dir = (u.pn >> 1) & 1, half = u.pn & 1;
;         const int row0 = u.pm * BM + wr * 64 + fr;
;         unsigned* lb_d = LB + (size_t)dir * M * LW;
;         const int ch0 = blk * 256 + half * 128 + wc * 32 + 8 * fq;
;         unsigned pba[4], pbx[4], pca[4];
; #pragma unroll
;         for (int n = 0; n < 2; ++n) { const f32x4 t0 = *(const f32x4*)(ba + dir * LW + ch0 + 4 * n), t1 = *(const f32x4*)(bx + dir * LW + ch0 + 4 * n), t2 = *(const f32x4*)(cA + dir * LW + ch0 + 4 * n);
;             pca[2 * n] = pk2(t2[0], t2[1]); pca[2 * n + 1] = pk2(t2[2], t2[3]);
;             constexpr float NL = -1.4426950408889634f;
;             pba[2 * n] = pk2(NL * t0[0], NL * t0[1]); pba[2 * n + 1] = pk2(NL * t0[2], NL * t0[3]); pbx[2 * n] = pk2(NL * t1[0], NL * t1[1]); pbx[2 * n + 1] = pk2(NL * t1[2], NL * t1[3]); }
;         u32x4 ucw[2][2];
;     ...
;         GATES_UCLOAD(0, 0);
; #pragma unroll
;         for (int am = 0; am < 4; ++am) { const int ai = am >> 1, m0 = (am & 1) * 2;
;             if (am + 1 < 4) GATES_UCLOAD((am + 1) & 1, am + 1);
	v_mov_b32_e32 v171, v0
	s_lshl_b32 s1, s5, 8
	v_readfirstlane_b32 s19, v171
	s_ashr_i32 s5, s19, 2
	s_andn2_b32 s5, s5, 63
	s_bfe_u32 s0, s4, 0x10001
	s_add_i32 s1, s5, s1
	s_lshl_b32 s5, s4, 6
	s_lshl_b32 s4, s4, 7
	s_and_b32 s5, s5, 0xffffff00
	s_and_b32 s4, s4, 0x80
	s_or_b32 s4, s5, s4
	s_lshr_b32 s5, s19, 1
	v_lshrrev_b32_e32 v130, 1, v171
	s_and_b32 s5, s5, 0x60
	v_and_or_b32 v130, v130, 24, s4
	v_or_b32_e32 v132, s5, v130
	s_mul_i32 s19, s0, 0x2c00
	s_add_u32 s4, s42, s19
	v_ashrrev_i32_e32 v133, 31, v132
	s_addc_u32 s5, s43, 0
	v_lshlrev_b64 v[130:131], 2, v[132:133]
	v_lshl_add_u64 v[138:139], s[4:5], 0, v[130:131]
	s_add_u32 s4, s44, s19
	s_addc_u32 s5, s45, 0
	v_lshl_add_u64 v[152:153], s[4:5], 0, v[130:131]
	s_add_u32 s4, s46, s19
	s_addc_u32 s5, s47, 0
	v_lshl_add_u64 v[158:159], s[4:5], 0, v[130:131]
	global_load_dwordx4 v[134:137], v[138:139], off offset:16
	s_nop 0
	global_load_dwordx4 v[138:141], v[138:139], off
	s_nop 0
	global_load_dwordx4 v[142:145], v[152:153], off offset:16
	s_nop 0
	global_load_dwordx4 v[152:155], v[152:153], off
	s_nop 0
	global_load_dwordx4 v[190:193], v[158:159], off offset:16
	s_nop 0
	global_load_dwordx4 v[158:161], v[158:159], off
	s_mul_i32 s0, s0, 0x6300000
	v_and_or_b32 v173, v171, 15, s1
	s_add_u32 s0, s40, s0
	s_addc_u32 s1, s41, 0
	v_or_b32_e32 v183, 32, v173
	v_or_b32_e32 v174, 48, v173
	v_lshl_add_u64 v[230:231], v[132:133], 1, s[10:11]
	v_or_b32_e32 v232, 16, v173
	v_mad_i64_i32 v[222:223], s[24:25], v173, s9, v[230:231]
	v_mad_i64_i32 v[224:225], s[24:25], v183, s9, v[230:231]
	v_mad_i64_i32 v[226:227], s[24:25], v232, s9, v[230:231]
	v_mad_i64_i32 v[228:229], s[24:25], v174, s9, v[230:231]
	s_nop 1
	global_load_dwordx4 v[206:209], v[222:223], off
	global_load_dwordx4 v[210:213], v[224:225], off
	global_load_dwordx4 v[214:217], v[226:227], off
	global_load_dwordx4 v[218:221], v[228:229], off
	s_waitcnt vmcnt(4)
	v_mul_f32_e32 v134, 0xbfb8aa3b, v134
	v_mul_f32_e32 v138, 0xbfb8aa3b, v138
	v_mul_f32_e32 v139, 0xbfb8aa3b, v139
	v_mul_f32_e32 v135, 0xbfb8aa3b, v135
	v_bfe_u32 v162, v158, 16, 1
	v_add3_u32 v172, v158, v162, s8
	v_bfe_u32 v158, v159, 16, 1
	v_add3_u32 v158, v159, v158, s8
	v_and_b32_e32 v166, 0xffff0000, v158
	v_bfe_u32 v158, v160, 16, 1
	v_add3_u32 v178, v160, v158, s8
	v_bfe_u32 v158, v161, 16, 1
	v_add3_u32 v158, v161, v158, s8
	v_and_b32_e32 v161, 0xffff0000, v158
	v_bfe_u32 v158, v138, 16, 1
	v_add3_u32 v170, v138, v158, s8
	v_bfe_u32 v138, v139, 16, 1
	v_add3_u32 v138, v139, v138, s8
	v_and_b32_e32 v168, 0xffff0000, v138
	v_mul_f32_e32 v138, 0xbfb8aa3b, v140
	v_mul_f32_e32 v139, 0xbfb8aa3b, v141
	v_bfe_u32 v140, v138, 16, 1
	v_add3_u32 v181, v138, v140, s8
	v_bfe_u32 v138, v139, 16, 1
	v_add3_u32 v138, v139, v138, s8
	v_and_b32_e32 v164, 0xffff0000, v138
	v_mul_f32_e32 v138, 0xbfb8aa3b, v152
	v_mul_f32_e32 v139, 0xbfb8aa3b, v153
	v_bfe_u32 v140, v138, 16, 1
	v_add3_u32 v185, v138, v140, s8
	v_bfe_u32 v138, v139, 16, 1
	v_add3_u32 v138, v139, v138, s8
	v_and_b32_e32 v169, 0xffff0000, v138
	v_mul_f32_e32 v138, 0xbfb8aa3b, v154
	v_mul_f32_e32 v139, 0xbfb8aa3b, v155
	v_bfe_u32 v140, v138, 16, 1
	v_add3_u32 v184, v138, v140, s8
	v_bfe_u32 v138, v139, 16, 1
	v_add3_u32 v138, v139, v138, s8
	v_and_b32_e32 v167, 0xffff0000, v138
	v_bfe_u32 v138, v190, 16, 1
	v_add3_u32 v177, v190, v138, s8
	v_bfe_u32 v138, v191, 16, 1
	v_add3_u32 v138, v191, v138, s8
	v_and_b32_e32 v160, 0xffff0000, v138
	v_bfe_u32 v138, v192, 16, 1
	v_add3_u32 v175, v192, v138, s8
	v_bfe_u32 v138, v193, 16, 1
	v_add3_u32 v138, v193, v138, s8
	v_and_b32_e32 v158, 0xffff0000, v138
	v_bfe_u32 v138, v134, 16, 1
	v_add3_u32 v180, v134, v138, s8
	v_bfe_u32 v134, v135, 16, 1
	v_add3_u32 v134, v135, v134, s8
	v_and_b32_e32 v163, 0xffff0000, v134
	v_mul_f32_e32 v134, 0xbfb8aa3b, v136
	v_mul_f32_e32 v135, 0xbfb8aa3b, v137
	v_bfe_u32 v136, v134, 16, 1
	v_add3_u32 v176, v134, v136, s8
	v_bfe_u32 v134, v135, 16, 1
	v_add3_u32 v134, v135, v134, s8
	v_and_b32_e32 v159, 0xffff0000, v134
	v_mul_f32_e32 v134, 0xbfb8aa3b, v142
	v_mul_f32_e32 v135, 0xbfb8aa3b, v143
	v_bfe_u32 v136, v134, 16, 1
	v_add3_u32 v182, v134, v136, s8
	v_bfe_u32 v134, v135, 16, 1
	v_add3_u32 v134, v135, v134, s8
	v_and_b32_e32 v165, 0xffff0000, v134
	v_mul_f32_e32 v134, 0xbfb8aa3b, v144
	v_mul_f32_e32 v135, 0xbfb8aa3b, v145
	v_bfe_u32 v136, v134, 16, 1
	v_add3_u32 v179, v134, v136, s8
	v_bfe_u32 v134, v135, 16, 1
	v_lshl_add_u64 v[154:155], v[132:133], 1, s[10:11]
	v_add3_u32 v134, v135, v134, s8
	v_mad_i64_i32 v[132:133], s[4:5], v173, s9, v[154:155]
	v_or_b32_e32 v190, 16, v173
	v_lshl_add_u64 v[152:153], s[0:1], 0, v[130:131]
	v_mad_i64_i32 v[130:131], s[0:1], v183, s9, v[154:155]
	v_and_b32_e32 v162, 0xffff0000, v134
	s_waitcnt vmcnt(0)
	v_mov_b32_e32 v142, v206
	v_mov_b32_e32 v143, v207
	v_mov_b32_e32 v144, v208
	v_mov_b32_e32 v145, v209
	v_mov_b32_e32 v134, v210
	v_mov_b32_e32 v135, v211
	v_mov_b32_e32 v136, v212
	v_mov_b32_e32 v137, v213
	v_mov_b32_e32 v138, v214
	v_mov_b32_e32 v139, v215
	v_mov_b32_e32 v140, v216
	v_mov_b32_e32 v141, v217
	v_mov_b32_e32 v130, v218
	v_mov_b32_e32 v131, v219
	v_mov_b32_e32 v132, v220
	v_mov_b32_e32 v133, v221
	v_and_b32_e32 v171, 0xffff0000, v170
	v_and_b32_e32 v170, 0xffff0000, v185
	v_fmamk_f32 v122, v122, 0xbfb8aa3b, v171
	v_exp_f32_e32 v122, v122
	v_fmamk_f32 v126, v126, 0xbfb8aa3b, v170
	v_exp_f32_e32 v126, v126
	v_fmamk_f32 v127, v127, 0xbfb8aa3b, v169
	v_fmamk_f32 v123, v123, 0xbfb8aa3b, v168
	v_exp_f32_e32 v127, v127
	v_exp_f32_e32 v123, v123
	v_add_f32_e32 v122, 1.0, v122
	v_rcp_f32_e32 v122, v122
	v_add_f32_e32 v126, 1.0, v126
	v_rcp_f32_e32 v126, v126
	v_add_f32_e32 v127, 1.0, v127
	v_add_f32_e32 v123, 1.0, v123
	v_rcp_f32_e32 v127, v127
	v_and_b32_e32 v172, 0xffff0000, v172
	v_rcp_f32_e32 v123, v123
	s_waitcnt vmcnt(3)
; __device__ __forceinline__ unsigned cvt_pk_bf16(float lo, float hi) { unsigned r; asm volatile("v_cvt_pk_bf16_f32 %0, %1, %2" : "=v"(r) : "v"(lo), "v"(hi)); return r; }
; __device__ __forceinline__ float fast_exp2(float x) { return __builtin_amdgcn_exp2f(x); }
; __device__ __forceinline__ float fast_rcp(float x) { return __builtin_amdgcn_rcpf(x); }
;     __device__ __forceinline__ void operator()(const f32x4 (&acc)[2][2][4][2], const Unit& u, int wr, int wc, int fr, int fq) const {
;     ...
;             for (int mm = 0; mm < 2; ++mm) { const int m = m0 + mm; const size_t ro = (size_t)(row0 + ai * HALF + m * 16) * LW + ch0;
;                 const unsigned uw[4] = {ucw[am & 1][mm].x, ucw[am & 1][mm].y, ucw[am & 1][mm].z, ucw[am & 1][mm].w};
;                 unsigned wv[8];
; #pragma unroll
;                 for (int n = 0; n < 2; ++n) {
; #pragma unroll
;                     for (int j = 0; j < 4; ++j) { const int pi = 2 * n + (j >> 1);
;                         const float ucv = (j & 1) ? bf_hi(uw[pi]) : bf_lo(uw[pi]), vb_a = (j & 1) ? bf_hi(pba[pi]) : bf_lo(pba[pi]), vb_x = (j & 1) ? bf_hi(pbx[pi]) : bf_lo(pbx[pi]);
;                         const float rr = fast_rcp(1.f + fast_exp2(fmaf(acc[ai][0][m][n][j], -1.4426950408889634f, vb_a))), ig = fast_rcp(1.f + fast_exp2(fmaf(acc[ai][1][m][n][j], -1.4426950408889634f, vb_x)));
;                         wv[4 * n + j] = cvt_pk_bf16(rr * ((j & 1) ? bf_hi(pca[pi]) : bf_lo(pca[pi])), ig * ucv); } }
;                 *(u32x4*)(lb_d + ro) = (u32x4){wv[0], wv[1], wv[2], wv[3]}; *(u32x4*)(lb_d + ro + 4) = (u32x4){wv[4], wv[5], wv[6], wv[7]}; }
	v_lshlrev_b32_e32 v185, 16, v142
	v_mul_f32_e32 v122, v122, v172
	v_mul_f32_e32 v126, v126, v185
	v_cvt_pk_bf16_f32 v192, v122, v126
	v_and_b32_e32 v122, 0xffff0000, v142
	v_mul_f32_e32 v122, v127, v122
	v_mul_f32_e32 v123, v123, v166
	v_cvt_pk_bf16_f32 v193, v123, v122
	v_and_b32_e32 v126, 0xffff0000, v181
	v_and_b32_e32 v122, 0xffff0000, v184
	v_fmamk_f32 v123, v124, 0xbfb8aa3b, v126
	v_fmamk_f32 v124, v128, 0xbfb8aa3b, v122
	v_exp_f32_e32 v124, v124
	v_exp_f32_e32 v123, v123
	v_fmamk_f32 v125, v125, 0xbfb8aa3b, v164
	v_exp_f32_e32 v125, v125
	v_add_f32_e32 v124, 1.0, v124
	v_fmamk_f32 v129, v129, 0xbfb8aa3b, v167
	v_rcp_f32_e32 v128, v124
	v_exp_f32_e32 v129, v129
	v_add_f32_e32 v123, 1.0, v123
	v_lshlrev_b32_e32 v127, 16, v143
	v_rcp_f32_e32 v123, v123
	v_add_f32_e32 v125, 1.0, v125
	v_mul_f32_e32 v127, v128, v127
	v_rcp_f32_e32 v125, v125
	v_add_f32_e32 v128, 1.0, v129
	v_rcp_f32_e32 v128, v128
	v_and_b32_e32 v124, 0xffff0000, v178
	v_mul_f32_e32 v123, v123, v124
	v_cvt_pk_bf16_f32 v194, v123, v127
	v_and_b32_e32 v123, 0xffff0000, v143
	v_mul_f32_e32 v125, v125, v161
	v_mul_f32_e32 v123, v128, v123
	v_cvt_pk_bf16_f32 v195, v125, v123
	v_and_b32_e32 v125, 0xffff0000, v180
	v_and_b32_e32 v123, 0xffff0000, v182
	v_fmamk_f32 v114, v114, 0xbfb8aa3b, v125
	v_exp_f32_e32 v114, v114
	v_fmamk_f32 v118, v118, 0xbfb8aa3b, v123
	v_exp_f32_e32 v118, v118
	v_fmamk_f32 v115, v115, 0xbfb8aa3b, v163
	v_fmamk_f32 v119, v119, 0xbfb8aa3b, v165
	v_exp_f32_e32 v115, v115
	v_exp_f32_e32 v119, v119
	v_add_f32_e32 v114, 1.0, v114
	v_rcp_f32_e32 v114, v114
	v_add_f32_e32 v118, 1.0, v118
	v_rcp_f32_e32 v118, v118
	v_add_f32_e32 v115, 1.0, v115
	v_add_f32_e32 v119, 1.0, v119
	v_rcp_f32_e32 v115, v115
	v_rcp_f32_e32 v119, v119
	v_and_b32_e32 v127, 0xffff0000, v177
	v_lshlrev_b32_e32 v128, 16, v144
	v_mul_f32_e32 v114, v114, v127
	v_mul_f32_e32 v118, v118, v128
	v_cvt_pk_bf16_f32 v142, v114, v118
	v_and_b32_e32 v114, 0xffff0000, v144
	v_mul_f32_e32 v115, v115, v160
	v_mul_f32_e32 v114, v119, v114
	v_and_b32_e32 v118, 0xffff0000, v176
	v_cvt_pk_bf16_f32 v143, v115, v114
	v_and_b32_e32 v115, 0xffff0000, v179
	v_fmamk_f32 v114, v116, 0xbfb8aa3b, v118
	v_exp_f32_e32 v114, v114
	v_fmamk_f32 v116, v120, 0xbfb8aa3b, v115
	v_exp_f32_e32 v116, v116
	v_fmamk_f32 v117, v117, 0xbfb8aa3b, v159
	v_add_f32_e32 v114, 1.0, v114
	v_rcp_f32_e32 v120, v114
	v_add_f32_e32 v114, 1.0, v116
	v_fmamk_f32 v121, v121, 0xbfb8aa3b, v162
	v_rcp_f32_e32 v116, v114
	v_exp_f32_e32 v117, v117
	v_exp_f32_e32 v121, v121
	v_fmamk_f32 v106, v106, 0xbfb8aa3b, v171
	v_fmamk_f32 v110, v110, 0xbfb8aa3b, v170
	v_lshlrev_b32_e32 v119, 16, v145
	v_exp_f32_e32 v106, v106
	v_exp_f32_e32 v110, v110
	v_mul_f32_e32 v116, v116, v119
	v_add_f32_e32 v117, 1.0, v117
	v_add_f32_e32 v119, 1.0, v121
	v_fmamk_f32 v107, v107, 0xbfb8aa3b, v168
	v_fmamk_f32 v111, v111, 0xbfb8aa3b, v169
	v_rcp_f32_e32 v117, v117
	v_rcp_f32_e32 v119, v119
	v_exp_f32_e32 v107, v107
	v_exp_f32_e32 v111, v111
	v_and_b32_e32 v114, 0xffff0000, v175
	v_add_f32_e32 v106, 1.0, v106
	v_add_f32_e32 v110, 1.0, v110
	v_mul_f32_e32 v120, v120, v114
	v_cvt_pk_bf16_f32 v144, v120, v116
	v_and_b32_e32 v116, 0xffff0000, v145
	v_rcp_f32_e32 v106, v106
	v_rcp_f32_e32 v110, v110
	v_mul_f32_e32 v117, v117, v158
	v_mul_f32_e32 v116, v119, v116
	s_movk_i32 s4, 0x2c00
	v_add_f32_e32 v107, 1.0, v107
	v_add_f32_e32 v111, 1.0, v111
	v_cvt_pk_bf16_f32 v145, v117, v116
	v_mad_i64_i32 v[116:117], s[0:1], v173, s4, v[152:153]
	v_rcp_f32_e32 v107, v107
	v_rcp_f32_e32 v111, v111
	global_store_dwordx4 v[116:117], v[192:195], off
	global_store_dwordx4 v[116:117], v[142:145], off offset:16
	s_waitcnt vmcnt(3)
	v_lshlrev_b32_e32 v116, 16, v138
	v_mul_f32_e32 v106, v106, v172
	v_mul_f32_e32 v110, v110, v116
	v_cvt_pk_bf16_f32 v106, v106, v110
	v_and_b32_e32 v110, 0xffff0000, v138
	v_mul_f32_e32 v107, v107, v166
	v_mul_f32_e32 v110, v111, v110
	v_cvt_pk_bf16_f32 v107, v107, v110
	v_fmamk_f32 v110, v112, 0xbfb8aa3b, v122
	v_exp_f32_e32 v110, v110
	v_fmamk_f32 v108, v108, 0xbfb8aa3b, v126
	v_exp_f32_e32 v108, v108
	v_fmamk_f32 v109, v109, 0xbfb8aa3b, v164
	v_add_f32_e32 v110, 1.0, v110
	v_fmamk_f32 v112, v113, 0xbfb8aa3b, v167
	v_rcp_f32_e32 v110, v110
	v_exp_f32_e32 v109, v109
	v_exp_f32_e32 v112, v112
	v_fmamk_f32 v98, v98, 0xbfb8aa3b, v125
	v_fmamk_f32 v102, v102, 0xbfb8aa3b, v123
	v_add_f32_e32 v108, 1.0, v108
	v_exp_f32_e32 v98, v98
	v_exp_f32_e32 v102, v102
	v_rcp_f32_e32 v108, v108
	v_lshlrev_b32_e32 v111, 16, v139
	v_fmamk_f32 v99, v99, 0xbfb8aa3b, v163
	v_fmamk_f32 v103, v103, 0xbfb8aa3b, v165
	v_mul_f32_e32 v110, v110, v111
	v_add_f32_e32 v109, 1.0, v109
	v_add_f32_e32 v111, 1.0, v112
	v_exp_f32_e32 v99, v99
	v_exp_f32_e32 v103, v103
	v_rcp_f32_e32 v109, v109
	v_rcp_f32_e32 v111, v111
	v_add_f32_e32 v98, 1.0, v98
	v_add_f32_e32 v102, 1.0, v102
	v_mul_f32_e32 v108, v108, v124
	v_rcp_f32_e32 v98, v98
	v_rcp_f32_e32 v102, v102
	v_cvt_pk_bf16_f32 v108, v108, v110
	v_and_b32_e32 v110, 0xffff0000, v139
	v_add_f32_e32 v99, 1.0, v99
	v_add_f32_e32 v103, 1.0, v103
	v_mul_f32_e32 v109, v109, v161
	v_mul_f32_e32 v110, v111, v110
	v_rcp_f32_e32 v99, v99
	v_rcp_f32_e32 v103, v103
	v_cvt_pk_bf16_f32 v109, v109, v110
	v_lshlrev_b32_e32 v110, 16, v140
	v_mul_f32_e32 v98, v98, v127
	v_mul_f32_e32 v102, v102, v110
	v_cvt_pk_bf16_f32 v98, v98, v102
	v_and_b32_e32 v102, 0xffff0000, v140
	v_mul_f32_e32 v99, v99, v160
	v_mul_f32_e32 v102, v103, v102
	v_cvt_pk_bf16_f32 v99, v99, v102
	v_fmamk_f32 v102, v104, 0xbfb8aa3b, v115
	v_exp_f32_e32 v102, v102
	v_fmamk_f32 v100, v100, 0xbfb8aa3b, v118
	v_exp_f32_e32 v100, v100
	v_fmamk_f32 v101, v101, 0xbfb8aa3b, v159
	v_add_f32_e32 v102, 1.0, v102
; __device__ __forceinline__ unsigned cvt_pk_bf16(float lo, float hi) { unsigned r; asm volatile("v_cvt_pk_bf16_f32 %0, %1, %2" : "=v"(r) : "v"(lo), "v"(hi)); return r; }
; __device__ __forceinline__ float fast_exp2(float x) { return __builtin_amdgcn_exp2f(x); }
; __device__ __forceinline__ float fast_rcp(float x) { return __builtin_amdgcn_rcpf(x); }
; #define GATES_UCLOAD(buf, am_) do { _Pragma("unroll") for (int mm = 0; mm < 2; ++mm) ucw[buf][mm] = *(const u32x4*)(UC + (size_t)(row0 + ((am_) >> 1) * HALF + (((am_) & 1) * 2 + mm) * 16) * LW + ch0); } while (0)
;     __device__ __forceinline__ void operator()(const f32x4 (&acc)[2][2][4][2], const Unit& u, int wr, int wc, int fr, int fq) const {
;     ...
;         for (int am = 0; am < 4; ++am) { const int ai = am >> 1, m0 = (am & 1) * 2;
;             if (am + 1 < 4) GATES_UCLOAD((am + 1) & 1, am + 1);
;             __builtin_amdgcn_sched_barrier(0);
; #pragma unroll
;             for (int mm = 0; mm < 2; ++mm) { const int m = m0 + mm; const size_t ro = (size_t)(row0 + ai * HALF + m * 16) * LW + ch0;
;                 const unsigned uw[4] = {ucw[am & 1][mm].x, ucw[am & 1][mm].y, ucw[am & 1][mm].z, ucw[am & 1][mm].w};
;                 unsigned wv[8];
; #pragma unroll
;                 for (int n = 0; n < 2; ++n) {
; #pragma unroll
;                     for (int j = 0; j < 4; ++j) { const int pi = 2 * n + (j >> 1);
;                         const float ucv = (j & 1) ? bf_hi(uw[pi]) : bf_lo(uw[pi]), vb_a = (j & 1) ? bf_hi(pba[pi]) : bf_lo(pba[pi]), vb_x = (j & 1) ? bf_hi(pbx[pi]) : bf_lo(pbx[pi]);
;                         const float rr = fast_rcp(1.f + fast_exp2(fmaf(acc[ai][0][m][n][j], -1.4426950408889634f, vb_a))), ig = fast_rcp(1.f + fast_exp2(fmaf(acc[ai][1][m][n][j], -1.4426950408889634f, vb_x)));
;                         wv[4 * n + j] = cvt_pk_bf16(rr * ((j & 1) ? bf_hi(pca[pi]) : bf_lo(pca[pi])), ig * ucv); } }
;                 *(u32x4*)(lb_d + ro) = (u32x4){wv[0], wv[1], wv[2], wv[3]}; *(u32x4*)(lb_d + ro + 4) = (u32x4){wv[4], wv[5], wv[6], wv[7]}; }
	v_fmamk_f32 v104, v105, 0xbfb8aa3b, v162
	v_rcp_f32_e32 v102, v102
	v_exp_f32_e32 v101, v101
	v_exp_f32_e32 v104, v104
	v_add_f32_e32 v100, 1.0, v100
	v_rcp_f32_e32 v100, v100
	v_lshlrev_b32_e32 v103, 16, v141
	v_mul_f32_e32 v102, v102, v103
	v_add_f32_e32 v101, 1.0, v101
	v_add_f32_e32 v103, 1.0, v104
	v_rcp_f32_e32 v101, v101
	v_rcp_f32_e32 v103, v103
	v_mul_f32_e32 v100, v100, v114
	v_cvt_pk_bf16_f32 v100, v100, v102
	v_and_b32_e32 v102, 0xffff0000, v141
	v_mul_f32_e32 v101, v101, v158
	v_mul_f32_e32 v102, v103, v102
	v_cvt_pk_bf16_f32 v101, v101, v102
	v_mad_i64_i32 v[102:103], s[0:1], v190, s4, v[152:153]
	global_store_dwordx4 v[102:103], v[106:109], off
	global_store_dwordx4 v[102:103], v[98:101], off offset:16
	s_nop 0
	v_add_u32_e32 v107, 0x80, v173
	v_add_u32_e32 v106, 0x90, v173
	v_mad_i64_i32 v[98:99], s[0:1], v107, s9, v[154:155]
	v_mad_i64_i32 v[100:101], s[0:1], v106, s9, v[154:155]
	global_load_dwordx4 v[102:105], v[98:99], off
	s_nop 0
	global_load_dwordx4 v[98:101], v[100:101], off
	v_fmamk_f32 v90, v90, 0xbfb8aa3b, v171
	v_fmamk_f32 v94, v94, 0xbfb8aa3b, v170
	v_exp_f32_e32 v90, v90
	v_exp_f32_e32 v94, v94
	v_fmamk_f32 v91, v91, 0xbfb8aa3b, v168
	v_fmamk_f32 v95, v95, 0xbfb8aa3b, v169
	v_exp_f32_e32 v91, v91
	v_exp_f32_e32 v95, v95
	v_add_f32_e32 v90, 1.0, v90
	v_add_f32_e32 v94, 1.0, v94
	v_rcp_f32_e32 v90, v90
	v_rcp_f32_e32 v94, v94
	v_add_f32_e32 v91, 1.0, v91
	v_add_f32_e32 v95, 1.0, v95
	v_rcp_f32_e32 v91, v91
	v_rcp_f32_e32 v95, v95
	v_lshlrev_b32_e32 v108, 16, v134
	v_mul_f32_e32 v90, v90, v172
	v_mul_f32_e32 v94, v94, v108
	v_cvt_pk_bf16_f32 v90, v90, v94
	v_and_b32_e32 v94, 0xffff0000, v134
	v_mul_f32_e32 v91, v91, v166
	v_mul_f32_e32 v94, v95, v94
	v_cvt_pk_bf16_f32 v91, v91, v94
	v_fmamk_f32 v94, v96, 0xbfb8aa3b, v122
	v_exp_f32_e32 v94, v94
	v_fmamk_f32 v92, v92, 0xbfb8aa3b, v126
	v_exp_f32_e32 v92, v92
	v_fmamk_f32 v93, v93, 0xbfb8aa3b, v164
	v_add_f32_e32 v94, 1.0, v94
	v_fmamk_f32 v96, v97, 0xbfb8aa3b, v167
	v_rcp_f32_e32 v94, v94
	v_exp_f32_e32 v93, v93
	v_exp_f32_e32 v96, v96
	v_fmamk_f32 v82, v82, 0xbfb8aa3b, v125
	v_fmamk_f32 v86, v86, 0xbfb8aa3b, v123
	v_add_f32_e32 v92, 1.0, v92
	v_exp_f32_e32 v82, v82
	v_exp_f32_e32 v86, v86
	v_rcp_f32_e32 v92, v92
	v_lshlrev_b32_e32 v95, 16, v135
	v_fmamk_f32 v83, v83, 0xbfb8aa3b, v163
	v_fmamk_f32 v87, v87, 0xbfb8aa3b, v165
	v_mul_f32_e32 v94, v94, v95
	v_add_f32_e32 v93, 1.0, v93
	v_add_f32_e32 v95, 1.0, v96
	v_exp_f32_e32 v83, v83
	v_exp_f32_e32 v87, v87
	v_rcp_f32_e32 v93, v93
	v_rcp_f32_e32 v95, v95
	v_add_f32_e32 v82, 1.0, v82
	v_add_f32_e32 v86, 1.0, v86
	v_mul_f32_e32 v92, v92, v124
	v_rcp_f32_e32 v82, v82
	v_rcp_f32_e32 v86, v86
	v_cvt_pk_bf16_f32 v92, v92, v94
	v_and_b32_e32 v94, 0xffff0000, v135
	v_add_f32_e32 v83, 1.0, v83
	v_add_f32_e32 v87, 1.0, v87
	v_mul_f32_e32 v93, v93, v161
	v_mul_f32_e32 v94, v95, v94
	v_rcp_f32_e32 v83, v83
	v_rcp_f32_e32 v87, v87
	v_cvt_pk_bf16_f32 v93, v93, v94
	v_lshlrev_b32_e32 v94, 16, v136
	v_mul_f32_e32 v82, v82, v127
	v_mul_f32_e32 v86, v86, v94
	v_cvt_pk_bf16_f32 v82, v82, v86
	v_and_b32_e32 v86, 0xffff0000, v136
	v_mul_f32_e32 v83, v83, v160
	v_mul_f32_e32 v86, v87, v86
	v_cvt_pk_bf16_f32 v83, v83, v86
	v_fmamk_f32 v86, v88, 0xbfb8aa3b, v115
	v_exp_f32_e32 v86, v86
	v_fmamk_f32 v84, v84, 0xbfb8aa3b, v118
	v_exp_f32_e32 v84, v84
	v_fmamk_f32 v85, v85, 0xbfb8aa3b, v159
	v_add_f32_e32 v86, 1.0, v86
	v_fmamk_f32 v88, v89, 0xbfb8aa3b, v162
	v_rcp_f32_e32 v86, v86
	v_exp_f32_e32 v85, v85
	v_exp_f32_e32 v88, v88
	v_add_f32_e32 v84, 1.0, v84
	v_fmamk_f32 v74, v74, 0xbfb8aa3b, v171
	v_fmamk_f32 v78, v78, 0xbfb8aa3b, v170
	v_rcp_f32_e32 v84, v84
	v_lshlrev_b32_e32 v87, 16, v137
	v_exp_f32_e32 v74, v74
	v_exp_f32_e32 v78, v78
	v_mul_f32_e32 v86, v86, v87
	v_add_f32_e32 v85, 1.0, v85
	v_add_f32_e32 v87, 1.0, v88
	v_fmamk_f32 v75, v75, 0xbfb8aa3b, v168
	v_fmamk_f32 v79, v79, 0xbfb8aa3b, v169
	v_rcp_f32_e32 v85, v85
	v_rcp_f32_e32 v87, v87
	v_exp_f32_e32 v75, v75
	v_exp_f32_e32 v79, v79
	v_mul_f32_e32 v84, v84, v114
	v_add_f32_e32 v74, 1.0, v74
	v_add_f32_e32 v78, 1.0, v78
	v_cvt_pk_bf16_f32 v84, v84, v86
	v_and_b32_e32 v86, 0xffff0000, v137
	v_rcp_f32_e32 v74, v74
	v_rcp_f32_e32 v78, v78
	v_mul_f32_e32 v85, v85, v158
	v_mul_f32_e32 v86, v87, v86
	v_add_f32_e32 v75, 1.0, v75
	v_add_f32_e32 v79, 1.0, v79
	v_cvt_pk_bf16_f32 v85, v85, v86
	v_mad_i64_i32 v[86:87], s[0:1], v183, s4, v[152:153]
	v_rcp_f32_e32 v75, v75
	v_rcp_f32_e32 v79, v79
	global_store_dwordx4 v[86:87], v[82:85], off offset:16
	v_mul_f32_e32 v74, v74, v172
	global_store_dwordx4 v[86:87], v[90:93], off
	s_waitcnt vmcnt(8)
; __device__ __forceinline__ unsigned cvt_pk_bf16(float lo, float hi) { unsigned r; asm volatile("v_cvt_pk_bf16_f32 %0, %1, %2" : "=v"(r) : "v"(lo), "v"(hi)); return r; }
; __device__ __forceinline__ float fast_exp2(float x) { return __builtin_amdgcn_exp2f(x); }
; __device__ __forceinline__ float fast_rcp(float x) { return __builtin_amdgcn_rcpf(x); }
; #define GATES_UCLOAD(buf, am_) do { _Pragma("unroll") for (int mm = 0; mm < 2; ++mm) ucw[buf][mm] = *(const u32x4*)(UC + (size_t)(row0 + ((am_) >> 1) * HALF + (((am_) & 1) * 2 + mm) * 16) * LW + ch0); } while (0)
;     __device__ __forceinline__ void operator()(const f32x4 (&acc)[2][2][4][2], const Unit& u, int wr, int wc, int fr, int fq) const {
;     ...
;         for (int am = 0; am < 4; ++am) { const int ai = am >> 1, m0 = (am & 1) * 2;
;             if (am + 1 < 4) GATES_UCLOAD((am + 1) & 1, am + 1);
;             __builtin_amdgcn_sched_barrier(0);
; #pragma unroll
;             for (int mm = 0; mm < 2; ++mm) { const int m = m0 + mm; const size_t ro = (size_t)(row0 + ai * HALF + m * 16) * LW + ch0;
;                 const unsigned uw[4] = {ucw[am & 1][mm].x, ucw[am & 1][mm].y, ucw[am & 1][mm].z, ucw[am & 1][mm].w};
;                 unsigned wv[8];
; #pragma unroll
;                 for (int n = 0; n < 2; ++n) {
; #pragma unroll
;                     for (int j = 0; j < 4; ++j) { const int pi = 2 * n + (j >> 1);
;                         const float ucv = (j & 1) ? bf_hi(uw[pi]) : bf_lo(uw[pi]), vb_a = (j & 1) ? bf_hi(pba[pi]) : bf_lo(pba[pi]), vb_x = (j & 1) ? bf_hi(pbx[pi]) : bf_lo(pbx[pi]);
;                         const float rr = fast_rcp(1.f + fast_exp2(fmaf(acc[ai][0][m][n][j], -1.4426950408889634f, vb_a))), ig = fast_rcp(1.f + fast_exp2(fmaf(acc[ai][1][m][n][j], -1.4426950408889634f, vb_x)));
;                         wv[4 * n + j] = cvt_pk_bf16(rr * ((j & 1) ? bf_hi(pca[pi]) : bf_lo(pca[pi])), ig * ucv); } }
;                 *(u32x4*)(lb_d + ro) = (u32x4){wv[0], wv[1], wv[2], wv[3]}; *(u32x4*)(lb_d + ro + 4) = (u32x4){wv[4], wv[5], wv[6], wv[7]}; }
	v_lshlrev_b32_e32 v82, 16, v130
	v_mul_f32_e32 v78, v78, v82
	v_cvt_pk_bf16_f32 v74, v74, v78
	v_and_b32_e32 v78, 0xffff0000, v130
	v_mul_f32_e32 v75, v75, v166
	v_mul_f32_e32 v78, v79, v78
	v_cvt_pk_bf16_f32 v75, v75, v78
	v_fmamk_f32 v78, v80, 0xbfb8aa3b, v122
	v_exp_f32_e32 v78, v78
	v_fmamk_f32 v76, v76, 0xbfb8aa3b, v126
	v_exp_f32_e32 v76, v76
	v_fmamk_f32 v77, v77, 0xbfb8aa3b, v164
	v_add_f32_e32 v78, 1.0, v78
	v_fmamk_f32 v80, v81, 0xbfb8aa3b, v167
	v_rcp_f32_e32 v78, v78
	v_exp_f32_e32 v77, v77
	v_exp_f32_e32 v80, v80
	v_fmamk_f32 v66, v66, 0xbfb8aa3b, v125
	v_fmamk_f32 v70, v70, 0xbfb8aa3b, v123
	v_add_f32_e32 v76, 1.0, v76
	v_exp_f32_e32 v66, v66
	v_exp_f32_e32 v70, v70
	v_rcp_f32_e32 v76, v76
	v_lshlrev_b32_e32 v79, 16, v131
	v_fmamk_f32 v67, v67, 0xbfb8aa3b, v163
	v_fmamk_f32 v71, v71, 0xbfb8aa3b, v165
	v_mul_f32_e32 v78, v78, v79
	v_add_f32_e32 v77, 1.0, v77
	v_add_f32_e32 v79, 1.0, v80
	v_exp_f32_e32 v67, v67
	v_exp_f32_e32 v71, v71
	v_rcp_f32_e32 v77, v77
	v_rcp_f32_e32 v79, v79
	v_add_f32_e32 v66, 1.0, v66
	v_add_f32_e32 v70, 1.0, v70
	v_mul_f32_e32 v76, v76, v124
	v_rcp_f32_e32 v66, v66
	v_rcp_f32_e32 v70, v70
	v_cvt_pk_bf16_f32 v76, v76, v78
	v_and_b32_e32 v78, 0xffff0000, v131
	v_add_f32_e32 v67, 1.0, v67
	v_add_f32_e32 v71, 1.0, v71
	v_mul_f32_e32 v77, v77, v161
	v_mul_f32_e32 v78, v79, v78
	v_rcp_f32_e32 v67, v67
	v_rcp_f32_e32 v71, v71
	v_cvt_pk_bf16_f32 v77, v77, v78
	v_lshlrev_b32_e32 v78, 16, v132
	v_mul_f32_e32 v66, v66, v127
	v_mul_f32_e32 v70, v70, v78
	v_cvt_pk_bf16_f32 v66, v66, v70
	v_and_b32_e32 v70, 0xffff0000, v132
	v_mul_f32_e32 v67, v67, v160
	v_mul_f32_e32 v70, v71, v70
	v_cvt_pk_bf16_f32 v67, v67, v70
	v_fmamk_f32 v70, v72, 0xbfb8aa3b, v115
	v_exp_f32_e32 v70, v70
	v_fmamk_f32 v68, v68, 0xbfb8aa3b, v118
	v_exp_f32_e32 v68, v68
	v_fmamk_f32 v69, v69, 0xbfb8aa3b, v159
	v_add_f32_e32 v70, 1.0, v70
	v_fmamk_f32 v72, v73, 0xbfb8aa3b, v162
	v_rcp_f32_e32 v70, v70
	v_exp_f32_e32 v69, v69
	v_exp_f32_e32 v72, v72
	v_add_f32_e32 v68, 1.0, v68
	v_rcp_f32_e32 v68, v68
	v_lshlrev_b32_e32 v71, 16, v133
	v_mul_f32_e32 v70, v70, v71
	v_add_f32_e32 v69, 1.0, v69
	v_add_f32_e32 v71, 1.0, v72
	v_rcp_f32_e32 v69, v69
	v_rcp_f32_e32 v71, v71
	v_mul_f32_e32 v68, v68, v114
	v_cvt_pk_bf16_f32 v68, v68, v70
	v_and_b32_e32 v70, 0xffff0000, v133
	v_mul_f32_e32 v69, v69, v158
	v_mul_f32_e32 v70, v71, v70
	v_cvt_pk_bf16_f32 v69, v69, v70
	v_mad_i64_i32 v[70:71], s[0:1], v174, s4, v[152:153]
	global_store_dwordx4 v[70:71], v[74:77], off
	global_store_dwordx4 v[70:71], v[66:69], off offset:16
	s_nop 0
	v_add_u32_e32 v75, 0xa0, v173
	v_add_u32_e32 v74, 0xb0, v173
	v_mad_i64_i32 v[66:67], s[0:1], v75, s9, v[154:155]
	v_mad_i64_i32 v[68:69], s[0:1], v74, s9, v[154:155]
	global_load_dwordx4 v[70:73], v[66:67], off
	s_nop 0
	global_load_dwordx4 v[66:69], v[68:69], off
	v_fmamk_f32 v58, v58, 0xbfb8aa3b, v171
	v_fmamk_f32 v62, v62, 0xbfb8aa3b, v170
	v_exp_f32_e32 v58, v58
	v_exp_f32_e32 v62, v62
	v_fmamk_f32 v59, v59, 0xbfb8aa3b, v168
	v_fmamk_f32 v63, v63, 0xbfb8aa3b, v169
	v_exp_f32_e32 v59, v59
	v_exp_f32_e32 v63, v63
	v_add_f32_e32 v58, 1.0, v58
	v_add_f32_e32 v62, 1.0, v62
	v_rcp_f32_e32 v58, v58
	v_rcp_f32_e32 v62, v62
	v_add_f32_e32 v59, 1.0, v59
	v_add_f32_e32 v63, 1.0, v63
	v_rcp_f32_e32 v59, v59
	v_rcp_f32_e32 v63, v63
	s_waitcnt vmcnt(7)
	v_lshlrev_b32_e32 v76, 16, v102
	v_mul_f32_e32 v58, v58, v172
	v_mul_f32_e32 v62, v62, v76
	v_cvt_pk_bf16_f32 v58, v58, v62
	v_and_b32_e32 v62, 0xffff0000, v102
	v_mul_f32_e32 v59, v59, v166
	v_mul_f32_e32 v62, v63, v62
	v_cvt_pk_bf16_f32 v59, v59, v62
	v_fmamk_f32 v62, v64, 0xbfb8aa3b, v122
	v_exp_f32_e32 v62, v62
	v_fmamk_f32 v60, v60, 0xbfb8aa3b, v126
	v_exp_f32_e32 v60, v60
	v_fmamk_f32 v61, v61, 0xbfb8aa3b, v164
	v_add_f32_e32 v62, 1.0, v62
	v_fmamk_f32 v64, v65, 0xbfb8aa3b, v167
	v_rcp_f32_e32 v62, v62
	v_exp_f32_e32 v61, v61
	v_exp_f32_e32 v64, v64
	v_fmamk_f32 v50, v50, 0xbfb8aa3b, v125
	v_fmamk_f32 v54, v54, 0xbfb8aa3b, v123
	v_add_f32_e32 v60, 1.0, v60
	v_exp_f32_e32 v50, v50
	v_exp_f32_e32 v54, v54
	v_rcp_f32_e32 v60, v60
	v_lshlrev_b32_e32 v63, 16, v103
	v_fmamk_f32 v51, v51, 0xbfb8aa3b, v163
	v_fmamk_f32 v55, v55, 0xbfb8aa3b, v165
	v_mul_f32_e32 v62, v62, v63
	v_add_f32_e32 v61, 1.0, v61
	v_add_f32_e32 v63, 1.0, v64
	v_exp_f32_e32 v51, v51
	v_exp_f32_e32 v55, v55
	v_rcp_f32_e32 v61, v61
	v_rcp_f32_e32 v63, v63
	v_add_f32_e32 v50, 1.0, v50
	v_add_f32_e32 v54, 1.0, v54
	v_mul_f32_e32 v60, v60, v124
	v_rcp_f32_e32 v50, v50
	v_rcp_f32_e32 v54, v54
	v_cvt_pk_bf16_f32 v60, v60, v62
	v_and_b32_e32 v62, 0xffff0000, v103
	v_add_f32_e32 v51, 1.0, v51
	v_add_f32_e32 v55, 1.0, v55
	v_mul_f32_e32 v61, v61, v161
	v_mul_f32_e32 v62, v63, v62
	v_rcp_f32_e32 v51, v51
	v_rcp_f32_e32 v55, v55
	v_cvt_pk_bf16_f32 v61, v61, v62
	v_lshlrev_b32_e32 v62, 16, v104
	v_mul_f32_e32 v50, v50, v127
	v_mul_f32_e32 v54, v54, v62
	v_cvt_pk_bf16_f32 v50, v50, v54
	v_and_b32_e32 v54, 0xffff0000, v104
	v_mul_f32_e32 v51, v51, v160
	v_mul_f32_e32 v54, v55, v54
	v_cvt_pk_bf16_f32 v51, v51, v54
	v_fmamk_f32 v54, v56, 0xbfb8aa3b, v115
	v_exp_f32_e32 v54, v54
	v_fmamk_f32 v52, v52, 0xbfb8aa3b, v118
	v_exp_f32_e32 v52, v52
	v_fmamk_f32 v53, v53, 0xbfb8aa3b, v159
	v_add_f32_e32 v54, 1.0, v54
	v_fmamk_f32 v56, v57, 0xbfb8aa3b, v162
	v_rcp_f32_e32 v54, v54
	v_exp_f32_e32 v53, v53
	v_exp_f32_e32 v56, v56
	v_add_f32_e32 v52, 1.0, v52
	v_fmamk_f32 v42, v42, 0xbfb8aa3b, v171
	v_fmamk_f32 v46, v46, 0xbfb8aa3b, v170
	v_rcp_f32_e32 v52, v52
	v_lshlrev_b32_e32 v55, 16, v105
	v_exp_f32_e32 v42, v42
	v_exp_f32_e32 v46, v46
	v_mul_f32_e32 v54, v54, v55
	v_add_f32_e32 v53, 1.0, v53
	v_add_f32_e32 v55, 1.0, v56
	v_fmamk_f32 v43, v43, 0xbfb8aa3b, v168
	v_fmamk_f32 v47, v47, 0xbfb8aa3b, v169
	v_rcp_f32_e32 v53, v53
	v_rcp_f32_e32 v55, v55
	v_exp_f32_e32 v43, v43
	v_exp_f32_e32 v47, v47
	v_mul_f32_e32 v52, v52, v114
	v_add_f32_e32 v42, 1.0, v42
	v_add_f32_e32 v46, 1.0, v46
	v_cvt_pk_bf16_f32 v52, v52, v54
	v_and_b32_e32 v54, 0xffff0000, v105
	v_rcp_f32_e32 v42, v42
	v_rcp_f32_e32 v46, v46
	v_mul_f32_e32 v53, v53, v158
	v_mul_f32_e32 v54, v55, v54
	v_add_f32_e32 v43, 1.0, v43
	v_add_f32_e32 v47, 1.0, v47
	v_cvt_pk_bf16_f32 v53, v53, v54
	v_mad_i64_i32 v[54:55], s[0:1], v107, s4, v[152:153]
	v_rcp_f32_e32 v43, v43
	v_rcp_f32_e32 v47, v47
	global_store_dwordx4 v[54:55], v[50:53], off offset:16
	v_mul_f32_e32 v42, v42, v172
	global_store_dwordx4 v[54:55], v[58:61], off
	s_waitcnt vmcnt(8)
; __device__ __forceinline__ unsigned cvt_pk_bf16(float lo, float hi) { unsigned r; asm volatile("v_cvt_pk_bf16_f32 %0, %1, %2" : "=v"(r) : "v"(lo), "v"(hi)); return r; }
; __device__ __forceinline__ float fast_exp2(float x) { return __builtin_amdgcn_exp2f(x); }
; __device__ __forceinline__ float fast_rcp(float x) { return __builtin_amdgcn_rcpf(x); }
; #define GATES_UCLOAD(buf, am_) do { _Pragma("unroll") for (int mm = 0; mm < 2; ++mm) ucw[buf][mm] = *(const u32x4*)(UC + (size_t)(row0 + ((am_) >> 1) * HALF + (((am_) & 1) * 2 + mm) * 16) * LW + ch0); } while (0)
;     __device__ __forceinline__ void operator()(const f32x4 (&acc)[2][2][4][2], const Unit& u, int wr, int wc, int fr, int fq) const {
;     ...
;         for (int am = 0; am < 4; ++am) { const int ai = am >> 1, m0 = (am & 1) * 2;
;             if (am + 1 < 4) GATES_UCLOAD((am + 1) & 1, am + 1);
;             __builtin_amdgcn_sched_barrier(0);
; #pragma unroll
;             for (int mm = 0; mm < 2; ++mm) { const int m = m0 + mm; const size_t ro = (size_t)(row0 + ai * HALF + m * 16) * LW + ch0;
;                 const unsigned uw[4] = {ucw[am & 1][mm].x, ucw[am & 1][mm].y, ucw[am & 1][mm].z, ucw[am & 1][mm].w};
;                 unsigned wv[8];
; #pragma unroll
;                 for (int n = 0; n < 2; ++n) {
; #pragma unroll
;                     for (int j = 0; j < 4; ++j) { const int pi = 2 * n + (j >> 1);
;                         const float ucv = (j & 1) ? bf_hi(uw[pi]) : bf_lo(uw[pi]), vb_a = (j & 1) ? bf_hi(pba[pi]) : bf_lo(pba[pi]), vb_x = (j & 1) ? bf_hi(pbx[pi]) : bf_lo(pbx[pi]);
;                         const float rr = fast_rcp(1.f + fast_exp2(fmaf(acc[ai][0][m][n][j], -1.4426950408889634f, vb_a))), ig = fast_rcp(1.f + fast_exp2(fmaf(acc[ai][1][m][n][j], -1.4426950408889634f, vb_x)));
;                         wv[4 * n + j] = cvt_pk_bf16(rr * ((j & 1) ? bf_hi(pca[pi]) : bf_lo(pca[pi])), ig * ucv); } }
;                 *(u32x4*)(lb_d + ro) = (u32x4){wv[0], wv[1], wv[2], wv[3]}; *(u32x4*)(lb_d + ro + 4) = (u32x4){wv[4], wv[5], wv[6], wv[7]}; }
;             __builtin_amdgcn_sched_barrier(0);
;         }
	v_lshlrev_b32_e32 v50, 16, v98
	v_mul_f32_e32 v46, v46, v50
	v_cvt_pk_bf16_f32 v42, v42, v46
	v_and_b32_e32 v46, 0xffff0000, v98
	v_mul_f32_e32 v43, v43, v166
	v_mul_f32_e32 v46, v47, v46
	v_cvt_pk_bf16_f32 v43, v43, v46
	v_fmamk_f32 v46, v48, 0xbfb8aa3b, v122
	v_exp_f32_e32 v46, v46
	v_fmamk_f32 v44, v44, 0xbfb8aa3b, v126
	v_exp_f32_e32 v44, v44
	v_fmamk_f32 v45, v45, 0xbfb8aa3b, v164
	v_add_f32_e32 v46, 1.0, v46
	v_fmamk_f32 v48, v49, 0xbfb8aa3b, v167
	v_rcp_f32_e32 v46, v46
	v_exp_f32_e32 v45, v45
	v_exp_f32_e32 v48, v48
	v_fmamk_f32 v34, v34, 0xbfb8aa3b, v125
	v_fmamk_f32 v38, v38, 0xbfb8aa3b, v123
	v_add_f32_e32 v44, 1.0, v44
	v_exp_f32_e32 v34, v34
	v_exp_f32_e32 v38, v38
	v_rcp_f32_e32 v44, v44
	v_lshlrev_b32_e32 v47, 16, v99
	v_fmamk_f32 v35, v35, 0xbfb8aa3b, v163
	v_fmamk_f32 v39, v39, 0xbfb8aa3b, v165
	v_mul_f32_e32 v46, v46, v47
	v_add_f32_e32 v45, 1.0, v45
	v_add_f32_e32 v47, 1.0, v48
	v_exp_f32_e32 v35, v35
	v_exp_f32_e32 v39, v39
	v_rcp_f32_e32 v45, v45
	v_rcp_f32_e32 v47, v47
	v_add_f32_e32 v34, 1.0, v34
	v_add_f32_e32 v38, 1.0, v38
	v_mul_f32_e32 v44, v44, v124
	v_rcp_f32_e32 v34, v34
	v_rcp_f32_e32 v38, v38
	v_cvt_pk_bf16_f32 v44, v44, v46
	v_and_b32_e32 v46, 0xffff0000, v99
	v_add_f32_e32 v35, 1.0, v35
	v_add_f32_e32 v39, 1.0, v39
	v_mul_f32_e32 v45, v45, v161
	v_mul_f32_e32 v46, v47, v46
	v_rcp_f32_e32 v35, v35
	v_rcp_f32_e32 v39, v39
	v_cvt_pk_bf16_f32 v45, v45, v46
	v_lshlrev_b32_e32 v46, 16, v100
	v_mul_f32_e32 v34, v34, v127
	v_mul_f32_e32 v38, v38, v46
	v_cvt_pk_bf16_f32 v34, v34, v38
	v_and_b32_e32 v38, 0xffff0000, v100
	v_mul_f32_e32 v35, v35, v160
	v_mul_f32_e32 v38, v39, v38
	v_cvt_pk_bf16_f32 v35, v35, v38
	v_fmamk_f32 v38, v40, 0xbfb8aa3b, v115
	v_exp_f32_e32 v38, v38
	v_fmamk_f32 v36, v36, 0xbfb8aa3b, v118
	v_exp_f32_e32 v36, v36
	v_fmamk_f32 v37, v37, 0xbfb8aa3b, v159
	v_add_f32_e32 v38, 1.0, v38
	v_fmamk_f32 v40, v41, 0xbfb8aa3b, v162
	v_rcp_f32_e32 v38, v38
	v_exp_f32_e32 v37, v37
	v_exp_f32_e32 v40, v40
	v_add_f32_e32 v36, 1.0, v36
	v_rcp_f32_e32 v36, v36
	v_lshlrev_b32_e32 v39, 16, v101
	v_mul_f32_e32 v38, v38, v39
	v_add_f32_e32 v37, 1.0, v37
	v_add_f32_e32 v39, 1.0, v40
	v_rcp_f32_e32 v37, v37
	v_rcp_f32_e32 v39, v39
	v_mul_f32_e32 v36, v36, v114
	v_cvt_pk_bf16_f32 v36, v36, v38
	v_and_b32_e32 v38, 0xffff0000, v101
	v_mul_f32_e32 v37, v37, v158
	v_mul_f32_e32 v38, v39, v38
	v_cvt_pk_bf16_f32 v37, v37, v38
	v_mad_i64_i32 v[38:39], s[0:1], v106, s4, v[152:153]
	global_store_dwordx4 v[38:39], v[42:45], off
	global_store_dwordx4 v[38:39], v[34:37], off offset:16
	v_fmamk_f32 v26, v26, 0xbfb8aa3b, v171
	v_fmamk_f32 v30, v30, 0xbfb8aa3b, v170
	v_exp_f32_e32 v26, v26
	v_exp_f32_e32 v30, v30
	v_fmamk_f32 v27, v27, 0xbfb8aa3b, v168
	v_fmamk_f32 v31, v31, 0xbfb8aa3b, v169
	v_exp_f32_e32 v27, v27
	v_exp_f32_e32 v31, v31
	v_add_f32_e32 v26, 1.0, v26
	v_add_f32_e32 v30, 1.0, v30
	v_rcp_f32_e32 v26, v26
	v_rcp_f32_e32 v30, v30
	v_add_f32_e32 v27, 1.0, v27
	v_add_f32_e32 v31, 1.0, v31
	v_rcp_f32_e32 v27, v27
	v_rcp_f32_e32 v31, v31
	s_waitcnt vmcnt(5)
; __device__ __forceinline__ unsigned cvt_pk_bf16(float lo, float hi) { unsigned r; asm volatile("v_cvt_pk_bf16_f32 %0, %1, %2" : "=v"(r) : "v"(lo), "v"(hi)); return r; }
; __device__ __forceinline__ float fast_exp2(float x) { return __builtin_amdgcn_exp2f(x); }
; __device__ __forceinline__ float fast_rcp(float x) { return __builtin_amdgcn_rcpf(x); }
; #define GATES_UCLOAD(buf, am_) do { _Pragma("unroll") for (int mm = 0; mm < 2; ++mm) ucw[buf][mm] = *(const u32x4*)(UC + (size_t)(row0 + ((am_) >> 1) * HALF + (((am_) & 1) * 2 + mm) * 16) * LW + ch0); } while (0)
;     __device__ __forceinline__ void operator()(const f32x4 (&acc)[2][2][4][2], const Unit& u, int wr, int wc, int fr, int fq) const {
;     ...
;         for (int am = 0; am < 4; ++am) { const int ai = am >> 1, m0 = (am & 1) * 2;
;             if (am + 1 < 4) GATES_UCLOAD((am + 1) & 1, am + 1);
;             __builtin_amdgcn_sched_barrier(0);
; #pragma unroll
;             for (int mm = 0; mm < 2; ++mm) { const int m = m0 + mm; const size_t ro = (size_t)(row0 + ai * HALF + m * 16) * LW + ch0;
;                 const unsigned uw[4] = {ucw[am & 1][mm].x, ucw[am & 1][mm].y, ucw[am & 1][mm].z, ucw[am & 1][mm].w};
;                 unsigned wv[8];
; #pragma unroll
;                 for (int n = 0; n < 2; ++n) {
; #pragma unroll
;                     for (int j = 0; j < 4; ++j) { const int pi = 2 * n + (j >> 1);
;                         const float ucv = (j & 1) ? bf_hi(uw[pi]) : bf_lo(uw[pi]), vb_a = (j & 1) ? bf_hi(pba[pi]) : bf_lo(pba[pi]), vb_x = (j & 1) ? bf_hi(pbx[pi]) : bf_lo(pbx[pi]);
;                         const float rr = fast_rcp(1.f + fast_exp2(fmaf(acc[ai][0][m][n][j], -1.4426950408889634f, vb_a))), ig = fast_rcp(1.f + fast_exp2(fmaf(acc[ai][1][m][n][j], -1.4426950408889634f, vb_x)));
;                         wv[4 * n + j] = cvt_pk_bf16(rr * ((j & 1) ? bf_hi(pca[pi]) : bf_lo(pca[pi])), ig * ucv); } }
;                 *(u32x4*)(lb_d + ro) = (u32x4){wv[0], wv[1], wv[2], wv[3]}; *(u32x4*)(lb_d + ro + 4) = (u32x4){wv[4], wv[5], wv[6], wv[7]}; }
;             __builtin_amdgcn_sched_barrier(0);
;         }
	v_lshlrev_b32_e32 v34, 16, v70
	v_mul_f32_e32 v26, v26, v172
	v_mul_f32_e32 v30, v30, v34
	v_cvt_pk_bf16_f32 v26, v26, v30
	v_and_b32_e32 v30, 0xffff0000, v70
	v_mul_f32_e32 v27, v27, v166
	v_mul_f32_e32 v30, v31, v30
	v_cvt_pk_bf16_f32 v27, v27, v30
	v_fmamk_f32 v30, v32, 0xbfb8aa3b, v122
	v_exp_f32_e32 v30, v30
	v_fmamk_f32 v28, v28, 0xbfb8aa3b, v126
	v_exp_f32_e32 v28, v28
	v_fmamk_f32 v29, v29, 0xbfb8aa3b, v164
	v_add_f32_e32 v30, 1.0, v30
	v_fmamk_f32 v32, v33, 0xbfb8aa3b, v167
	v_rcp_f32_e32 v30, v30
	v_exp_f32_e32 v29, v29
	v_exp_f32_e32 v32, v32
	v_fmamk_f32 v18, v18, 0xbfb8aa3b, v125
	v_fmamk_f32 v22, v22, 0xbfb8aa3b, v123
	v_add_f32_e32 v28, 1.0, v28
	v_exp_f32_e32 v18, v18
	v_exp_f32_e32 v22, v22
	v_rcp_f32_e32 v28, v28
	v_lshlrev_b32_e32 v31, 16, v71
	v_fmamk_f32 v19, v19, 0xbfb8aa3b, v163
	v_fmamk_f32 v23, v23, 0xbfb8aa3b, v165
	v_mul_f32_e32 v30, v30, v31
	v_add_f32_e32 v29, 1.0, v29
	v_add_f32_e32 v31, 1.0, v32
	v_exp_f32_e32 v19, v19
	v_exp_f32_e32 v23, v23
	v_rcp_f32_e32 v29, v29
	v_rcp_f32_e32 v31, v31
	v_add_f32_e32 v18, 1.0, v18
	v_add_f32_e32 v22, 1.0, v22
	v_mul_f32_e32 v28, v28, v124
	v_rcp_f32_e32 v18, v18
	v_rcp_f32_e32 v22, v22
	v_cvt_pk_bf16_f32 v28, v28, v30
	v_and_b32_e32 v30, 0xffff0000, v71
	v_add_f32_e32 v19, 1.0, v19
	v_add_f32_e32 v23, 1.0, v23
	v_mul_f32_e32 v29, v29, v161
	v_mul_f32_e32 v30, v31, v30
	v_rcp_f32_e32 v19, v19
	v_rcp_f32_e32 v23, v23
	v_cvt_pk_bf16_f32 v29, v29, v30
	v_lshlrev_b32_e32 v30, 16, v72
	v_mul_f32_e32 v18, v18, v127
	v_mul_f32_e32 v22, v22, v30
	v_cvt_pk_bf16_f32 v18, v18, v22
	v_and_b32_e32 v22, 0xffff0000, v72
	v_mul_f32_e32 v19, v19, v160
	v_mul_f32_e32 v22, v23, v22
	v_cvt_pk_bf16_f32 v19, v19, v22
	v_fmamk_f32 v22, v24, 0xbfb8aa3b, v115
	v_exp_f32_e32 v22, v22
	v_fmamk_f32 v20, v20, 0xbfb8aa3b, v118
	v_exp_f32_e32 v20, v20
	v_fmamk_f32 v21, v21, 0xbfb8aa3b, v159
	v_add_f32_e32 v22, 1.0, v22
	v_fmamk_f32 v24, v25, 0xbfb8aa3b, v162
	v_rcp_f32_e32 v22, v22
	v_exp_f32_e32 v21, v21
	v_exp_f32_e32 v24, v24
	v_add_f32_e32 v20, 1.0, v20
	v_fmac_f32_e32 v171, 0xbfb8aa3b, v10
	v_fmac_f32_e32 v170, 0xbfb8aa3b, v14
	v_rcp_f32_e32 v20, v20
	v_lshlrev_b32_e32 v23, 16, v73
	v_exp_f32_e32 v10, v171
	v_exp_f32_e32 v14, v170
	v_mul_f32_e32 v22, v22, v23
	v_add_f32_e32 v21, 1.0, v21
	v_add_f32_e32 v23, 1.0, v24
	v_fmac_f32_e32 v168, 0xbfb8aa3b, v11
	v_fmac_f32_e32 v169, 0xbfb8aa3b, v15
	v_rcp_f32_e32 v21, v21
	v_rcp_f32_e32 v23, v23
	v_exp_f32_e32 v11, v168
	v_exp_f32_e32 v15, v169
	v_mul_f32_e32 v20, v20, v114
	v_add_f32_e32 v10, 1.0, v10
	v_add_f32_e32 v14, 1.0, v14
	v_cvt_pk_bf16_f32 v20, v20, v22
	v_and_b32_e32 v22, 0xffff0000, v73
	v_rcp_f32_e32 v10, v10
	v_rcp_f32_e32 v14, v14
	v_mul_f32_e32 v21, v21, v158
	v_mul_f32_e32 v22, v23, v22
	v_add_f32_e32 v11, 1.0, v11
	v_add_f32_e32 v15, 1.0, v15
	v_cvt_pk_bf16_f32 v21, v21, v22
	v_mad_i64_i32 v[22:23], s[0:1], v75, s4, v[152:153]
	v_rcp_f32_e32 v11, v11
	v_rcp_f32_e32 v15, v15
	global_store_dwordx4 v[22:23], v[18:21], off offset:16
	v_mul_f32_e32 v10, v10, v172
	global_store_dwordx4 v[22:23], v[26:29], off
	s_waitcnt vmcnt(6)
	v_lshlrev_b32_e32 v18, 16, v66
	v_mul_f32_e32 v14, v14, v18
	v_cvt_pk_bf16_f32 v10, v10, v14
	v_and_b32_e32 v14, 0xffff0000, v66
	v_mul_f32_e32 v11, v11, v166
	v_mul_f32_e32 v14, v15, v14
	v_fmac_f32_e32 v122, 0xbfb8aa3b, v16
	v_cvt_pk_bf16_f32 v11, v11, v14
	v_exp_f32_e32 v14, v122
	v_fmac_f32_e32 v126, 0xbfb8aa3b, v12
	v_exp_f32_e32 v12, v126
	v_fmac_f32_e32 v164, 0xbfb8aa3b, v13
	v_add_f32_e32 v14, 1.0, v14
	v_fmac_f32_e32 v167, 0xbfb8aa3b, v17
	v_rcp_f32_e32 v14, v14
	v_exp_f32_e32 v13, v164
	v_exp_f32_e32 v16, v167
	v_fmac_f32_e32 v125, 0xbfb8aa3b, v2
	v_fmac_f32_e32 v123, 0xbfb8aa3b, v6
	v_add_f32_e32 v12, 1.0, v12
	v_exp_f32_e32 v2, v125
	v_exp_f32_e32 v6, v123
	v_rcp_f32_e32 v12, v12
	v_lshlrev_b32_e32 v15, 16, v67
	v_fmac_f32_e32 v163, 0xbfb8aa3b, v3
	v_fmac_f32_e32 v165, 0xbfb8aa3b, v7
	v_mul_f32_e32 v14, v14, v15
	v_add_f32_e32 v13, 1.0, v13
	v_add_f32_e32 v15, 1.0, v16
	v_exp_f32_e32 v3, v163
	v_exp_f32_e32 v7, v165
	v_rcp_f32_e32 v13, v13
	v_rcp_f32_e32 v15, v15
	v_add_f32_e32 v2, 1.0, v2
	v_add_f32_e32 v6, 1.0, v6
	v_mul_f32_e32 v12, v12, v124
	v_rcp_f32_e32 v2, v2
	v_rcp_f32_e32 v6, v6
	v_cvt_pk_bf16_f32 v12, v12, v14
	v_and_b32_e32 v14, 0xffff0000, v67
	v_add_f32_e32 v3, 1.0, v3
	v_add_f32_e32 v7, 1.0, v7
	v_mul_f32_e32 v13, v13, v161
	v_mul_f32_e32 v14, v15, v14
	v_rcp_f32_e32 v3, v3
	v_rcp_f32_e32 v7, v7
	v_cvt_pk_bf16_f32 v13, v13, v14
	v_lshlrev_b32_e32 v14, 16, v68
	v_mul_f32_e32 v2, v2, v127
	v_mul_f32_e32 v6, v6, v14
	v_cvt_pk_bf16_f32 v2, v2, v6
	v_and_b32_e32 v6, 0xffff0000, v68
	v_mul_f32_e32 v3, v3, v160
	v_mul_f32_e32 v6, v7, v6
	v_fmac_f32_e32 v115, 0xbfb8aa3b, v8
	v_cvt_pk_bf16_f32 v3, v3, v6
	v_exp_f32_e32 v6, v115
	v_fmac_f32_e32 v118, 0xbfb8aa3b, v4
	v_exp_f32_e32 v4, v118
	v_fmac_f32_e32 v162, 0xbfb8aa3b, v9
	v_add_f32_e32 v6, 1.0, v6
	v_fmac_f32_e32 v159, 0xbfb8aa3b, v5
	v_rcp_f32_e32 v6, v6
	v_exp_f32_e32 v8, v162
	v_exp_f32_e32 v5, v159
	v_add_f32_e32 v4, 1.0, v4
	v_lshlrev_b32_e32 v7, 16, v69
	v_rcp_f32_e32 v4, v4
	v_mul_f32_e32 v6, v6, v7
	v_add_f32_e32 v7, 1.0, v8
	v_add_f32_e32 v5, 1.0, v5
	v_rcp_f32_e32 v5, v5
	v_rcp_f32_e32 v7, v7
	v_mul_f32_e32 v4, v4, v114
	v_cvt_pk_bf16_f32 v4, v4, v6
	v_and_b32_e32 v6, 0xffff0000, v69
	v_mul_f32_e32 v5, v5, v158
	v_mul_f32_e32 v6, v7, v6
	v_cvt_pk_bf16_f32 v5, v5, v6
	v_mad_i64_i32 v[6:7], s[0:1], v74, s4, v[152:153]
	global_store_dwordx4 v[6:7], v[10:13], off
	global_store_dwordx4 v[6:7], v[2:5], off offset:16
	s_add_i32 s52, s52, s95
	s_andn2_b64 vcc, exec, s[38:39]
	s_mov_b32 s4, s18
	s_mov_b32 s5, s48
	s_mov_b64 s[26:27], s[22:23]
	s_mov_b64 s[24:25], s[20:21]
	v_readlane_b32 s0, v255, 41
	v_readlane_b32 s20, v255, 43
	s_mov_b32 s90, 0x4c0000
	s_mov_b32 s91, 0xe0000
	s_mov_b32 s69, 0x220000
	s_mov_b32 s68, 0x120000
	s_mov_b32 s70, 0x800000
	v_readlane_b32 s1, v255, 42
	v_readlane_b32 s21, v255, 44
	s_cbranch_vccz .LBB9_872
